# P phase: decay rates via scalar loads issued at unit header (no dependent VMEM round trip at epilogue start); FFN-up: per-row sum-of-squares loads hoisted to the unit header into v241-v248
# speedup vs baseline: 1.0022x; 1.0022x over previous
; __device__ __forceinline__ bool unit_at(const GemmD& g, int G, int c, int i, int& pm, int& pn, int& z) {
;     const int L = i * G + c; const int per = g.nM * g.nN; if (L >= per * g.nZ) return false;
;     z = L / per; int wgid = L % per;
;     { const int q = per / NXCD, r = per % NXCD, xcd = wgid % NXCD, off = wgid / NXCD; wgid = (xcd < r ? xcd * (q + 1) : r * (q + 1) + (xcd - r) * q) + off; }
;     const int nig = WGM * g.nN, gid = wgid / nig, fm = gid * WGM, gsz = (g.nM - fm) < WGM ? (g.nM - fm) : WGM;
;     pm = fm + ((wgid % nig) % gsz); pn = (wgid % nig) / gsz; return true;
;     __device__ __forceinline__ void operator()(AccRef acc, int pm, int pn, int z, int wr, int wc, int fr, int fq) const {
;     ...
;         float rrow[2][4];
; #pragma unroll
;         for (int ai = 0; ai < 2; ++ai)
; #pragma unroll
;             for (int m = 0; m < 4; ++m) rrow[ai][m] = rsq[row0 + ai * HALF + m * 16];
.LBB0_199:
	v_readlane_b32 s100, v238, 57
	v_readlane_b32 s101, v238, 58
	v_lshl_add_u32 v250, s23, 8, v143
	v_ashrrev_i32_e32 v251, 31, v250
	s_nop 0
	v_lshl_add_u64 v[250:251], v[250:251], 2, s[100:101]
	global_load_dword v241, v[250:251], off
	global_load_dword v242, v[250:251], off offset:64
	global_load_dword v243, v[250:251], off offset:128
	global_load_dword v244, v[250:251], off offset:192
	global_load_dword v245, v[250:251], off offset:512
	global_load_dword v246, v[250:251], off offset:576
	global_load_dword v247, v[250:251], off offset:640
	global_load_dword v248, v[250:251], off offset:704
	s_add_i32 s19, s19, 1
	v_readlane_b32 s4, v240, 0
	s_mul_i32 s4, s19, s4
	s_add_i32 s4, s4, s53
	s_cmpk_lt_i32 s4, 0xb00
	s_cselect_b64 s[80:81], -1, 0
	s_cmpk_gt_i32 s4, 0xaff
	v_readlane_b32 s5, v240, 1
	s_cbranch_scc1 .LBB0_201
	s_mul_hi_i32 s5, s4, 0x2e8ba2e9
	s_lshr_b32 s26, s5, 31
	s_ashr_i32 s5, s5, 9
	s_add_i32 s5, s5, s26
	s_mulk_i32 s5, 0xb00
	s_sub_i32 s4, s4, s5
	s_sext_i32_i16 s5, s4
	s_bfe_u32 s5, s5, 0x3001c
	s_add_i32 s5, s4, s5
	s_sext_i32_i16 s26, s5
	s_and_b32 s5, s5, 0xfff8
	s_sub_i32 s4, s4, s5
	s_ashr_i32 s26, s26, 3
	s_sext_i32_i16 s5, s4
	s_cmp_lt_i32 s5, 0
	s_movk_i32 s5, 0x161
	s_cselect_b32 s5, s5, 0x160
	s_mul_i32 s4, s4, s5
	s_add_i32 s4, s4, s26
	s_sext_i32_i16 s5, s4
	s_mulk_i32 s5, 0xba3
	s_lshr_b32 s26, s5, 31
	s_ashr_i32 s5, s5, 19
	s_add_i32 s5, s5, s26
	s_lshl_b32 s26, s5, 2
	s_mulk_i32 s5, 0xb0
	s_sub_i32 s4, s4, s5
	s_sext_i32_i16 s5, s4
	s_bfe_u32 s5, s5, 0x2001d
	s_add_i32 s5, s4, s5
	s_sext_i32_i16 s27, s5
	s_and_b32 s5, s5, 0xfffc
	s_sub_i32 s4, s4, s5
	s_sext_i32_i16 s4, s4
	s_add_i32 s64, s26, s4
	s_ashr_i32 s66, s27, 2

; #define PG8_STAGE(bufoff, gbase, voff) do { _Pragma("unroll") for (int _i = 0; _i < 2; ++_i) \
;         __builtin_amdgcn_global_load_lds((const unsigned*)((const char*)(gbase) + (voff)[_i]), (LAS unsigned*)(lds + (bufoff) + ldsw + _i * 8192), 16, 0, 0); } while (0)
; #define PG8_LDA(dst, b, h) do { _Pragma("unroll") for (int m = 0; m < 4; ++m) _Pragma("unroll") for (int k = 0; k < 2; ++k) dst[m][k] = *(const LAS bf16x8*)(lds + PG8_SA(b, h) + aoff + m * 2048 + k * 1024); } while (0)
; #define PG8_LDB(dst, b, h) do { _Pragma("unroll") for (int n = 0; n < 2; ++n) _Pragma("unroll") for (int k = 0; k < 2; ++k) dst[n][k] = *(const LAS bf16x8*)(lds + PG8_SB(b, h) + boff + n * 2048 + k * 1024); } while (0)
; #define PG8_MMA(ai, bj, At, Bt) do { __builtin_amdgcn_s_setprio(1); _Pragma("unroll") for (int m = 0; m < 4; ++m) _Pragma("unroll") for (int n = 0; n < 2; ++n) _Pragma("unroll") for (int k = 0; k < 2; ++k) \
;         acc[ai][bj][m][n] = __builtin_amdgcn_mfma_f32_16x16x32_bf16(Bt[n][k], At[m][k], acc[ai][bj][m][n], 0, 0, 0); __builtin_amdgcn_s_setprio(0); } while (0)
; #define PG8_WAIT_V(n) asm volatile("s_waitcnt vmcnt(" #n ")" ::: "memory")
; #define PG8_WAIT_L(n) asm volatile("s_waitcnt lgkmcnt(" #n ")" ::: "memory")
; #define PG8_BAR __builtin_amdgcn_s_barrier()
; #define PG8_SCHED __builtin_amdgcn_sched_barrier(0)
; template <class Epi>
; __device__ __forceinline__ void gemm_phase(LAS unsigned char* lds, const GemmD g, const Epi& E, int G, int c) {
;     ...
;         for (int t = 0; t < nt; t += 2) {
;             const bool last = (t == nt - 2);
;             const char* a1 = cA + (size_t)(t + 1) * kstep;
;             const char* a2 = last ? nA : cA + (size_t)(t + 2) * kstep; const char* b2 = last ? nB : cB + (size_t)(t + 2) * kstep;
;             const char* a3 = a2 + kstep; const char* b3 = b2 + kstep;
;             PG8_LDB(B0, 0, 0); PG8_LDB(B1, 0, 1); PG8_SCHED; PG8_LDA(At, 0, 0); PG8_STAGE(PG8_SA(1, 1), a1 + hstepA, voffA);
;             PG8_WAIT_V(8); PG8_WAIT_L(0); PG8_BAR; PG8_MMA(0, 0, At, B0); PG8_MMA(0, 1, At, B1); PG8_BAR; PG8_SCHED;
;             PG8_LDA(At, 0, 1); PG8_STAGE(PG8_SB(0, 0), b2, voffB); PG8_STAGE(PG8_SB(0, 1), b2 + hstepB, voffB); PG8_STAGE(PG8_SA(0, 0), a2, voffA);
;             PG8_WAIT_V(8); PG8_WAIT_L(0); PG8_BAR; PG8_MMA(1, 0, At, B0); PG8_MMA(1, 1, At, B1); PG8_BAR; PG8_SCHED;
.LBB0_202:
	s_add_u32 s4, s42, 0xfff80080
	s_addc_u32 s5, s43, -1
	s_add_i32 s35, 0, 0x10000
	s_cmp_eq_u32 s33, 28
	s_cselect_b32 s5, s26, s5
	s_cselect_b32 s4, s27, s4
	v_add_u32_e32 v142, s35, v145
	s_cselect_b32 s87, s28, s31
	s_cselect_b32 s86, s29, s30
	s_add_i32 s36, 0, 0x14000
	ds_read_b128 v[138:141], v142
	ds_read_b128 v[152:155], v142 offset:1024
	ds_read_b128 v[156:159], v142 offset:2048
	ds_read_b128 v[160:163], v142 offset:3072
	v_add_u32_e32 v142, s36, v145
	ds_read_b128 v[164:167], v142
	ds_read_b128 v[168:171], v142 offset:1024
	ds_read_b128 v[172:175], v142 offset:2048
	ds_read_b128 v[180:183], v142 offset:3072
	v_lshl_add_u64 v[146:147], s[42:43], 0, v[134:135]
	s_add_i32 m0, s6, 0xc000
	ds_read_b128 v[184:187], v151
	ds_read_b128 v[188:191], v151 offset:1024
	ds_read_b128 v[192:195], v151 offset:2048
	ds_read_b128 v[210:213], v151 offset:3072
	ds_read_b128 v[214:217], v151 offset:4096
	ds_read_b128 v[218:221], v151 offset:5120
	ds_read_b128 v[222:225], v151 offset:6144
	ds_read_b128 v[226:229], v151 offset:7168
	global_load_lds_dwordx4 v[146:147], off
	v_lshl_add_u64 v[146:147], s[42:43], 0, v[136:137]
	s_add_i32 m0, s6, 0xe000
	s_nop 0
	global_load_lds_dwordx4 v[146:147], off
	s_cmp_lg_u32 s99, 0
	s_cbranch_scc1 .Lrw_FfnUp_0_r
	s_waitcnt vmcnt(8)
	s_branch .Lrw_FfnUp_0_d
.Lrw_FfnUp_0_r:
	s_waitcnt vmcnt(24)
.Lrw_FfnUp_0_d:
	s_waitcnt lgkmcnt(0)
	s_barrier
	s_setprio 1
	s_waitcnt lgkmcnt(0)
	v_mfma_f32_16x16x32_bf16 v[124:127], v[138:141], v[184:187], v[124:127]
	v_mfma_f32_16x16x32_bf16 v[116:119], v[156:159], v[184:187], v[116:119]
	v_mfma_f32_16x16x32_bf16 v[108:111], v[138:141], v[192:195], v[108:111]
	v_mfma_f32_16x16x32_bf16 v[100:103], v[156:159], v[192:195], v[100:103]
	v_mfma_f32_16x16x32_bf16 v[92:95], v[138:141], v[214:217], v[92:95]
	v_mfma_f32_16x16x32_bf16 v[84:87], v[156:159], v[214:217], v[84:87]
	v_mfma_f32_16x16x32_bf16 v[76:79], v[138:141], v[222:225], v[76:79]
	v_mfma_f32_16x16x32_bf16 v[68:71], v[156:159], v[222:225], v[68:71]
	v_mfma_f32_16x16x32_bf16 v[124:127], v[152:155], v[188:191], v[124:127]
	v_mfma_f32_16x16x32_bf16 v[116:119], v[160:163], v[188:191], v[116:119]
	v_mfma_f32_16x16x32_bf16 v[108:111], v[152:155], v[210:213], v[108:111]
	v_mfma_f32_16x16x32_bf16 v[100:103], v[160:163], v[210:213], v[100:103]
	v_mfma_f32_16x16x32_bf16 v[92:95], v[152:155], v[218:221], v[92:95]
	v_mfma_f32_16x16x32_bf16 v[84:87], v[160:163], v[218:221], v[84:87]
	v_mfma_f32_16x16x32_bf16 v[76:79], v[152:155], v[226:229], v[76:79]
	v_mfma_f32_16x16x32_bf16 v[68:71], v[160:163], v[226:229], v[68:71]
	s_setprio 0
	s_setprio 1
	v_mfma_f32_16x16x32_bf16 v[120:123], v[164:167], v[184:187], v[120:123]
	v_mfma_f32_16x16x32_bf16 v[112:115], v[172:175], v[184:187], v[112:115]
	v_mfma_f32_16x16x32_bf16 v[104:107], v[164:167], v[192:195], v[104:107]
	v_mfma_f32_16x16x32_bf16 v[96:99], v[172:175], v[192:195], v[96:99]
	v_mfma_f32_16x16x32_bf16 v[88:91], v[164:167], v[214:217], v[88:91]
	v_mfma_f32_16x16x32_bf16 v[80:83], v[172:175], v[214:217], v[80:83]
	v_mfma_f32_16x16x32_bf16 v[72:75], v[164:167], v[222:225], v[72:75]
	v_mfma_f32_16x16x32_bf16 v[64:67], v[172:175], v[222:225], v[64:67]
	v_mfma_f32_16x16x32_bf16 v[120:123], v[168:171], v[188:191], v[120:123]
	v_mfma_f32_16x16x32_bf16 v[112:115], v[180:183], v[188:191], v[112:115]
	v_mfma_f32_16x16x32_bf16 v[104:107], v[168:171], v[210:213], v[104:107]
	v_mfma_f32_16x16x32_bf16 v[96:99], v[180:183], v[210:213], v[96:99]
	v_mfma_f32_16x16x32_bf16 v[88:91], v[168:171], v[218:221], v[88:91]
	v_mfma_f32_16x16x32_bf16 v[80:83], v[180:183], v[218:221], v[80:83]
	v_mfma_f32_16x16x32_bf16 v[72:75], v[168:171], v[226:229], v[72:75]
	v_mfma_f32_16x16x32_bf16 v[64:67], v[180:183], v[226:229], v[64:67]
	s_setprio 0
	s_barrier
	s_add_i32 s35, s35, s2
	v_lshl_add_u64 v[146:147], s[86:87], 0, v[178:179]
	s_mov_b32 m0, s35
	ds_read_b128 v[184:187], v151 offset:16384
	ds_read_b128 v[188:191], v151 offset:17408
	ds_read_b128 v[192:195], v151 offset:18432
	ds_read_b128 v[210:213], v151 offset:19456
	ds_read_b128 v[214:217], v151 offset:20480
	ds_read_b128 v[218:221], v151 offset:21504
	ds_read_b128 v[222:225], v151 offset:22528
	ds_read_b128 v[226:229], v151 offset:23552
	global_load_lds_dwordx4 v[146:147], off
	s_add_i32 m0, s35, 0x2000
	s_add_u32 s38, s86, 0x80000
	v_lshl_add_u64 v[198:199], s[86:87], 0, v[128:129]
	s_addc_u32 s39, s87, 0
	s_add_i32 s35, s36, s2
	global_load_lds_dwordx4 v[198:199], off
	v_lshl_add_u64 v[230:231], s[38:39], 0, v[178:179]
	s_mov_b32 m0, s35
	v_lshl_add_u64 v[232:233], s[4:5], 0, v[130:131]
	global_load_lds_dwordx4 v[230:231], off
	v_lshl_add_u64 v[230:231], s[38:39], 0, v[128:129]
	s_add_i32 m0, s35, 0x2000
	s_nop 0
	global_load_lds_dwordx4 v[230:231], off
	v_lshl_add_u64 v[230:231], s[4:5], 0, v[132:133]
	s_mov_b32 m0, s6
	s_nop 0
	global_load_lds_dwordx4 v[230:231], off
	s_mov_b32 m0, s9
	s_nop 0
	global_load_lds_dwordx4 v[232:233], off
	s_cmp_lg_u32 s99, 0
	s_cbranch_scc1 .Lrw_FfnUp_1_r
	s_waitcnt vmcnt(8)
	s_branch .Lrw_FfnUp_1_d
.Lrw_FfnUp_1_r:
	s_waitcnt vmcnt(24)
	s_mov_b32 s99, 0
; #define PG8_STAGE(bufoff, gbase, voff) do { _Pragma("unroll") for (int _i = 0; _i < 2; ++_i) \
;         __builtin_amdgcn_global_load_lds((const unsigned*)((const char*)(gbase) + (voff)[_i]), (LAS unsigned*)(lds + (bufoff) + ldsw + _i * 8192), 16, 0, 0); } while (0)
; #define PG8_LDA(dst, b, h) do { _Pragma("unroll") for (int m = 0; m < 4; ++m) _Pragma("unroll") for (int k = 0; k < 2; ++k) dst[m][k] = *(const LAS bf16x8*)(lds + PG8_SA(b, h) + aoff + m * 2048 + k * 1024); } while (0)
; #define PG8_LDB(dst, b, h) do { _Pragma("unroll") for (int n = 0; n < 2; ++n) _Pragma("unroll") for (int k = 0; k < 2; ++k) dst[n][k] = *(const LAS bf16x8*)(lds + PG8_SB(b, h) + boff + n * 2048 + k * 1024); } while (0)
; #define PG8_MMA(ai, bj, At, Bt) do { __builtin_amdgcn_s_setprio(1); _Pragma("unroll") for (int m = 0; m < 4; ++m) _Pragma("unroll") for (int n = 0; n < 2; ++n) _Pragma("unroll") for (int k = 0; k < 2; ++k) \
;         acc[ai][bj][m][n] = __builtin_amdgcn_mfma_f32_16x16x32_bf16(Bt[n][k], At[m][k], acc[ai][bj][m][n], 0, 0, 0); __builtin_amdgcn_s_setprio(0); } while (0)
; #define PG8_WAIT_V(n) asm volatile("s_waitcnt vmcnt(" #n ")" ::: "memory")
; #define PG8_WAIT_L(n) asm volatile("s_waitcnt lgkmcnt(" #n ")" ::: "memory")
; #define PG8_BAR __builtin_amdgcn_s_barrier()
; #define PG8_SCHED __builtin_amdgcn_sched_barrier(0)
; template <class Epi>
; __device__ __forceinline__ void gemm_phase(LAS unsigned char* lds, const GemmD g, const Epi& E, int G, int c) {
;     ...
;             PG8_WAIT_V(8); PG8_WAIT_L(0); PG8_BAR; PG8_MMA(1, 0, At, B0); PG8_MMA(1, 1, At, B1); PG8_BAR; PG8_SCHED;
;             PG8_LDB(B0, 1, 0); PG8_LDB(B1, 1, 1); PG8_SCHED; PG8_LDA(At, 1, 0); PG8_STAGE(PG8_SA(0, 1), a2 + hstepA, voffA);
;             PG8_WAIT_V(8); PG8_WAIT_L(0); PG8_BAR; PG8_MMA(0, 0, At, B0); PG8_MMA(0, 1, At, B1); PG8_BAR; PG8_SCHED;
.Lrw_FfnUp_1_d:
	s_waitcnt lgkmcnt(0)
	s_barrier
	s_setprio 1
	s_waitcnt lgkmcnt(0)
	v_mfma_f32_16x16x32_bf16 v[60:63], v[138:141], v[184:187], v[60:63]
	v_mfma_f32_16x16x32_bf16 v[52:55], v[156:159], v[184:187], v[52:55]
	v_mfma_f32_16x16x32_bf16 v[44:47], v[138:141], v[192:195], v[44:47]
	v_mfma_f32_16x16x32_bf16 v[36:39], v[156:159], v[192:195], v[36:39]
	v_mfma_f32_16x16x32_bf16 v[28:31], v[138:141], v[214:217], v[28:31]
	v_mfma_f32_16x16x32_bf16 v[20:23], v[156:159], v[214:217], v[20:23]
	v_mfma_f32_16x16x32_bf16 v[12:15], v[138:141], v[222:225], v[12:15]
	v_mfma_f32_16x16x32_bf16 v[4:7], v[156:159], v[222:225], v[4:7]
	v_mfma_f32_16x16x32_bf16 v[60:63], v[152:155], v[188:191], v[60:63]
	v_mfma_f32_16x16x32_bf16 v[52:55], v[160:163], v[188:191], v[52:55]
	v_mfma_f32_16x16x32_bf16 v[44:47], v[152:155], v[210:213], v[44:47]
	v_mfma_f32_16x16x32_bf16 v[36:39], v[160:163], v[210:213], v[36:39]
	v_mfma_f32_16x16x32_bf16 v[28:31], v[152:155], v[218:221], v[28:31]
	v_mfma_f32_16x16x32_bf16 v[20:23], v[160:163], v[218:221], v[20:23]
	v_mfma_f32_16x16x32_bf16 v[12:15], v[152:155], v[226:229], v[12:15]
	v_mfma_f32_16x16x32_bf16 v[4:7], v[160:163], v[226:229], v[4:7]
	s_setprio 0
	s_setprio 1
	v_mfma_f32_16x16x32_bf16 v[56:59], v[164:167], v[184:187], v[56:59]
	v_mfma_f32_16x16x32_bf16 v[48:51], v[172:175], v[184:187], v[48:51]
	v_mfma_f32_16x16x32_bf16 v[40:43], v[164:167], v[192:195], v[40:43]
	v_mfma_f32_16x16x32_bf16 v[32:35], v[172:175], v[192:195], v[32:35]
	v_mfma_f32_16x16x32_bf16 v[24:27], v[164:167], v[214:217], v[24:27]
	v_mfma_f32_16x16x32_bf16 v[16:19], v[172:175], v[214:217], v[16:19]
	v_mfma_f32_16x16x32_bf16 v[8:11], v[164:167], v[222:225], v[8:11]
	v_mfma_f32_16x16x32_bf16 v[0:3], v[172:175], v[222:225], v[0:3]
	v_mfma_f32_16x16x32_bf16 v[56:59], v[168:171], v[188:191], v[56:59]
	v_mfma_f32_16x16x32_bf16 v[48:51], v[180:183], v[188:191], v[48:51]
	v_mfma_f32_16x16x32_bf16 v[40:43], v[168:171], v[210:213], v[40:43]
	v_mfma_f32_16x16x32_bf16 v[32:35], v[180:183], v[210:213], v[32:35]
	v_mfma_f32_16x16x32_bf16 v[24:27], v[168:171], v[218:221], v[24:27]
	v_mfma_f32_16x16x32_bf16 v[16:19], v[180:183], v[218:221], v[16:19]
	v_mfma_f32_16x16x32_bf16 v[8:11], v[168:171], v[226:229], v[8:11]
	v_mfma_f32_16x16x32_bf16 v[0:3], v[180:183], v[226:229], v[0:3]
	s_setprio 0
	s_barrier
	s_add_i32 s35, 0, 0x18000
	v_add_u32_e32 v142, s35, v145
	s_add_i32 s36, 0, 0x1c000
	ds_read_b128 v[138:141], v142
	ds_read_b128 v[152:155], v142 offset:1024
	ds_read_b128 v[156:159], v142 offset:2048
	ds_read_b128 v[160:163], v142 offset:3072
	v_add_u32_e32 v142, s36, v145
	ds_read_b128 v[164:167], v142
	ds_read_b128 v[168:171], v142 offset:1024
	ds_read_b128 v[172:175], v142 offset:2048
	ds_read_b128 v[180:183], v142 offset:3072
	s_add_u32 s4, s4, 0x80000
	s_addc_u32 s5, s5, 0
	s_mov_b32 m0, s10
	v_lshl_add_u64 v[234:235], s[4:5], 0, v[132:133]
	ds_read_b128 v[184:187], v151 offset:32768
	ds_read_b128 v[188:191], v151 offset:33792
	ds_read_b128 v[192:195], v151 offset:34816
	ds_read_b128 v[210:213], v151 offset:35840
	ds_read_b128 v[214:217], v151 offset:36864
	ds_read_b128 v[218:221], v151 offset:37888
	ds_read_b128 v[222:225], v151 offset:38912
	ds_read_b128 v[226:229], v151 offset:39936
	global_load_lds_dwordx4 v[234:235], off
	v_lshl_add_u64 v[234:235], s[4:5], 0, v[130:131]
	s_mov_b32 m0, s11
	s_nop 0
	global_load_lds_dwordx4 v[234:235], off
	s_waitcnt vmcnt(8)
	s_waitcnt lgkmcnt(0)
	s_barrier
	s_setprio 1
	s_waitcnt lgkmcnt(0)
	v_mfma_f32_16x16x32_bf16 v[124:127], v[138:141], v[184:187], v[124:127]
	v_mfma_f32_16x16x32_bf16 v[116:119], v[156:159], v[184:187], v[116:119]
	v_mfma_f32_16x16x32_bf16 v[108:111], v[138:141], v[192:195], v[108:111]
	v_mfma_f32_16x16x32_bf16 v[100:103], v[156:159], v[192:195], v[100:103]
	v_mfma_f32_16x16x32_bf16 v[92:95], v[138:141], v[214:217], v[92:95]
	v_mfma_f32_16x16x32_bf16 v[84:87], v[156:159], v[214:217], v[84:87]
	v_mfma_f32_16x16x32_bf16 v[76:79], v[138:141], v[222:225], v[76:79]
	v_mfma_f32_16x16x32_bf16 v[68:71], v[156:159], v[222:225], v[68:71]
	v_mfma_f32_16x16x32_bf16 v[124:127], v[152:155], v[188:191], v[124:127]
	v_mfma_f32_16x16x32_bf16 v[116:119], v[160:163], v[188:191], v[116:119]
	v_mfma_f32_16x16x32_bf16 v[108:111], v[152:155], v[210:213], v[108:111]
	v_mfma_f32_16x16x32_bf16 v[100:103], v[160:163], v[210:213], v[100:103]
	v_mfma_f32_16x16x32_bf16 v[92:95], v[152:155], v[218:221], v[92:95]
	v_mfma_f32_16x16x32_bf16 v[84:87], v[160:163], v[218:221], v[84:87]
	v_mfma_f32_16x16x32_bf16 v[76:79], v[152:155], v[226:229], v[76:79]
	v_mfma_f32_16x16x32_bf16 v[68:71], v[160:163], v[226:229], v[68:71]
	s_setprio 0
	s_setprio 1
	v_mfma_f32_16x16x32_bf16 v[120:123], v[164:167], v[184:187], v[120:123]
	v_mfma_f32_16x16x32_bf16 v[112:115], v[172:175], v[184:187], v[112:115]
	v_mfma_f32_16x16x32_bf16 v[104:107], v[164:167], v[192:195], v[104:107]
	v_mfma_f32_16x16x32_bf16 v[96:99], v[172:175], v[192:195], v[96:99]
	v_mfma_f32_16x16x32_bf16 v[88:91], v[164:167], v[214:217], v[88:91]
	v_mfma_f32_16x16x32_bf16 v[80:83], v[172:175], v[214:217], v[80:83]
	v_mfma_f32_16x16x32_bf16 v[72:75], v[164:167], v[222:225], v[72:75]
	v_mfma_f32_16x16x32_bf16 v[64:67], v[172:175], v[222:225], v[64:67]
	v_mfma_f32_16x16x32_bf16 v[120:123], v[168:171], v[188:191], v[120:123]
	v_mfma_f32_16x16x32_bf16 v[112:115], v[180:183], v[188:191], v[112:115]
	v_mfma_f32_16x16x32_bf16 v[104:107], v[168:171], v[210:213], v[104:107]
	v_mfma_f32_16x16x32_bf16 v[96:99], v[180:183], v[210:213], v[96:99]
	v_mfma_f32_16x16x32_bf16 v[88:91], v[168:171], v[218:221], v[88:91]
	v_mfma_f32_16x16x32_bf16 v[80:83], v[180:183], v[218:221], v[80:83]
	v_mfma_f32_16x16x32_bf16 v[72:75], v[168:171], v[226:229], v[72:75]
	v_mfma_f32_16x16x32_bf16 v[64:67], v[180:183], v[226:229], v[64:67]
	s_setprio 0
	s_barrier
; #define PG8_STAGE(bufoff, gbase, voff) do { _Pragma("unroll") for (int _i = 0; _i < 2; ++_i) \
;         __builtin_amdgcn_global_load_lds((const unsigned*)((const char*)(gbase) + (voff)[_i]), (LAS unsigned*)(lds + (bufoff) + ldsw + _i * 8192), 16, 0, 0); } while (0)
; #define PG8_LDA(dst, b, h) do { _Pragma("unroll") for (int m = 0; m < 4; ++m) _Pragma("unroll") for (int k = 0; k < 2; ++k) dst[m][k] = *(const LAS bf16x8*)(lds + PG8_SA(b, h) + aoff + m * 2048 + k * 1024); } while (0)
; #define PG8_MMA(ai, bj, At, Bt) do { __builtin_amdgcn_s_setprio(1); _Pragma("unroll") for (int m = 0; m < 4; ++m) _Pragma("unroll") for (int n = 0; n < 2; ++n) _Pragma("unroll") for (int k = 0; k < 2; ++k) \
;         acc[ai][bj][m][n] = __builtin_amdgcn_mfma_f32_16x16x32_bf16(Bt[n][k], At[m][k], acc[ai][bj][m][n], 0, 0, 0); __builtin_amdgcn_s_setprio(0); } while (0)
; #define PG8_WAIT_V(n) asm volatile("s_waitcnt vmcnt(" #n ")" ::: "memory")
; #define PG8_WAIT_L(n) asm volatile("s_waitcnt lgkmcnt(" #n ")" ::: "memory")
; #define PG8_BAR __builtin_amdgcn_s_barrier()
; #define PG8_SCHED __builtin_amdgcn_sched_barrier(0)
; template <class Epi>
; __device__ __forceinline__ void gemm_phase(LAS unsigned char* lds, const GemmD g, const Epi& E, int G, int c) {
;     ...
;             PG8_LDA(At, 1, 1); PG8_STAGE(PG8_SB(1, 0), b3, voffB); PG8_STAGE(PG8_SB(1, 1), b3 + hstepB, voffB); PG8_STAGE(PG8_SA(1, 0), a3, voffA);
;             PG8_WAIT_V(8); PG8_WAIT_L(0); PG8_BAR; PG8_MMA(1, 0, At, B0); PG8_MMA(1, 1, At, B1); PG8_BAR; PG8_SCHED;
;         }
;         if (wr == 0) PG8_BAR;
;     __device__ __forceinline__ void operator()(AccRef acc, int pm, int pn, int z, int wr, int wc, int fr, int fq) const {
;     ...
;         float rrow[2][4];
; #pragma unroll
;         for (int ai = 0; ai < 2; ++ai)
; #pragma unroll
;             for (int m = 0; m < 4; ++m) rrow[ai][m] = rsq[row0 + ai * HALF + m * 16];
; #pragma unroll
;         for (int ai = 0; ai < 2; ++ai)
; #pragma unroll
;             for (int m = 0; m < 4; ++m) rrow[ai][m] = 1.0f / sqrtf(rrow[ai][m] * (1.0f / DM) + EPS);
	s_add_i32 s4, s35, s2
	v_lshl_add_u64 v[146:147], v[146:147], 0, s[48:49]
	s_mov_b32 m0, s4
	ds_read_b128 v[184:187], v151 offset:49152
	ds_read_b128 v[188:191], v151 offset:50176
	ds_read_b128 v[192:195], v151 offset:51200
	ds_read_b128 v[210:213], v151 offset:52224
	ds_read_b128 v[214:217], v151 offset:53248
	ds_read_b128 v[218:221], v151 offset:54272
	ds_read_b128 v[222:225], v151 offset:55296
	ds_read_b128 v[226:229], v151 offset:56320
	global_load_lds_dwordx4 v[146:147], off
	s_add_i32 m0, s4, 0x2000
	s_add_u32 s4, s86, 0x80080
	v_lshl_add_u64 v[146:147], v[198:199], 0, s[48:49]
	s_addc_u32 s5, s87, 0
	s_add_i32 s35, s36, s2
	global_load_lds_dwordx4 v[146:147], off
	v_lshl_add_u64 v[146:147], s[4:5], 0, v[178:179]
	s_mov_b32 m0, s35
	s_nop 0
	global_load_lds_dwordx4 v[146:147], off
	v_lshl_add_u64 v[146:147], s[4:5], 0, v[128:129]
	s_add_i32 m0, s35, 0x2000
	s_nop 0
	global_load_lds_dwordx4 v[146:147], off
	v_lshl_add_u64 v[146:147], v[230:231], 0, s[48:49]
	s_mov_b32 m0, s16
	s_nop 0
	global_load_lds_dwordx4 v[146:147], off
	v_lshl_add_u64 v[146:147], v[232:233], 0, s[48:49]
	s_mov_b32 m0, s17
	s_nop 0
	global_load_lds_dwordx4 v[146:147], off
	s_waitcnt vmcnt(8)
	s_waitcnt lgkmcnt(0)
	s_barrier
	s_setprio 1
	s_waitcnt lgkmcnt(0)
	v_mfma_f32_16x16x32_bf16 v[60:63], v[138:141], v[184:187], v[60:63]
	v_mfma_f32_16x16x32_bf16 v[52:55], v[156:159], v[184:187], v[52:55]
	v_mfma_f32_16x16x32_bf16 v[44:47], v[138:141], v[192:195], v[44:47]
	v_mfma_f32_16x16x32_bf16 v[36:39], v[156:159], v[192:195], v[36:39]
	v_mfma_f32_16x16x32_bf16 v[28:31], v[138:141], v[214:217], v[28:31]
	v_mfma_f32_16x16x32_bf16 v[20:23], v[156:159], v[214:217], v[20:23]
	v_mfma_f32_16x16x32_bf16 v[12:15], v[138:141], v[222:225], v[12:15]
	v_mfma_f32_16x16x32_bf16 v[4:7], v[156:159], v[222:225], v[4:7]
	v_mfma_f32_16x16x32_bf16 v[60:63], v[152:155], v[188:191], v[60:63]
	v_mfma_f32_16x16x32_bf16 v[52:55], v[160:163], v[188:191], v[52:55]
	v_mfma_f32_16x16x32_bf16 v[44:47], v[152:155], v[210:213], v[44:47]
	v_mfma_f32_16x16x32_bf16 v[36:39], v[160:163], v[210:213], v[36:39]
	v_mfma_f32_16x16x32_bf16 v[28:31], v[152:155], v[218:221], v[28:31]
	v_mfma_f32_16x16x32_bf16 v[20:23], v[160:163], v[218:221], v[20:23]
	v_mfma_f32_16x16x32_bf16 v[12:15], v[152:155], v[226:229], v[12:15]
	v_mfma_f32_16x16x32_bf16 v[4:7], v[160:163], v[226:229], v[4:7]
	s_setprio 0
	s_setprio 1
	v_mfma_f32_16x16x32_bf16 v[56:59], v[164:167], v[184:187], v[56:59]
	v_mfma_f32_16x16x32_bf16 v[48:51], v[172:175], v[184:187], v[48:51]
	v_mfma_f32_16x16x32_bf16 v[40:43], v[164:167], v[192:195], v[40:43]
	v_mfma_f32_16x16x32_bf16 v[32:35], v[172:175], v[192:195], v[32:35]
	v_mfma_f32_16x16x32_bf16 v[24:27], v[164:167], v[214:217], v[24:27]
	v_mfma_f32_16x16x32_bf16 v[16:19], v[172:175], v[214:217], v[16:19]
	v_mfma_f32_16x16x32_bf16 v[8:11], v[164:167], v[222:225], v[8:11]
	v_mfma_f32_16x16x32_bf16 v[0:3], v[172:175], v[222:225], v[0:3]
	v_mfma_f32_16x16x32_bf16 v[56:59], v[168:171], v[188:191], v[56:59]
	v_mfma_f32_16x16x32_bf16 v[48:51], v[180:183], v[188:191], v[48:51]
	v_mfma_f32_16x16x32_bf16 v[40:43], v[168:171], v[210:213], v[40:43]
	v_mfma_f32_16x16x32_bf16 v[32:35], v[180:183], v[210:213], v[32:35]
	v_mfma_f32_16x16x32_bf16 v[24:27], v[168:171], v[218:221], v[24:27]
	v_mfma_f32_16x16x32_bf16 v[16:19], v[180:183], v[218:221], v[16:19]
	v_mfma_f32_16x16x32_bf16 v[8:11], v[168:171], v[226:229], v[8:11]
	v_mfma_f32_16x16x32_bf16 v[0:3], v[180:183], v[226:229], v[0:3]
	s_setprio 0
	s_barrier
	s_add_i32 s33, s33, 2
	s_add_u32 s42, s42, 0x100
	s_addc_u32 s43, s43, 0
	s_add_u32 s30, s30, 0x100
	s_addc_u32 s31, s31, 0
	s_cmp_gt_u32 s33, 29
	s_cbranch_scc0 .LBB0_202
	s_and_b64 vcc, exec, s[46:47]
	s_cbranch_vccz .LBB0_205
	s_barrier
.LBB0_205:
	v_lshl_add_u32 v152, s23, 8, v143
	v_readlane_b32 s4, v238, 57
	v_ashrrev_i32_e32 v153, 31, v152
	v_readlane_b32 s5, v238, 58
	v_or_b32_e32 v146, 16, v152
	v_ashrrev_i32_e32 v147, 31, v146
	v_lshl_add_u64 v[156:157], v[152:153], 2, s[4:5]
	v_mov_b32_e32 v158, v241
	v_mov_b32_e32 v144, v247
	v_lshl_add_u64 v[138:139], v[146:147], 2, s[4:5]
	v_mov_b32_e32 v159, v242
	v_or_b32_e32 v140, 32, v152
	v_ashrrev_i32_e32 v141, 31, v140
	v_lshl_add_u64 v[138:139], v[140:141], 2, s[4:5]
	v_mov_b32_e32 v160, v243
	v_mov_b32_e32 v150, v245
	v_mov_b32_e32 v142, v248
	v_or_b32_e32 v138, 48, v152
	v_ashrrev_i32_e32 v139, 31, v138
	v_lshl_add_u64 v[154:155], v[138:139], 2, s[4:5]
	v_mov_b32_e32 v155, v244
	v_add_u32_e32 v153, 0x80, v152
	v_mov_b32_e32 v148, v246
	v_add_u32_e32 v147, 0x90, v152
	v_add_u32_e32 v141, 0xa0, v152
	v_add_u32_e32 v139, 0xb0, v152
	v_fmamk_f32 v154, v158, 0x3a000000, v201
	v_cmp_gt_f32_e32 vcc, s51, v154
	v_mul_f32_e32 v156, 0x4f800000, v154
	v_fmamk_f32 v144, v144, 0x3a000000, v201
	v_cndmask_b32_e32 v154, v154, v156, vcc
	v_sqrt_f32_e32 v156, v154
	v_fmamk_f32 v150, v150, 0x3a000000, v201
	v_add_u32_e32 v157, -1, v156
	v_fma_f32 v158, -v157, v156, v154
	v_cmp_ge_f32_e64 s[42:43], 0, v158
	v_add_u32_e32 v158, 1, v156
	v_fmamk_f32 v155, v155, 0x3a000000, v201
	v_cndmask_b32_e64 v157, v156, v157, s[42:43]
	v_fma_f32 v156, -v158, v156, v154
	v_cmp_lt_f32_e64 s[42:43], 0, v156
	v_fmamk_f32 v148, v148, 0x3a000000, v201
	v_fmamk_f32 v142, v142, 0x3a000000, v201
	v_cndmask_b32_e64 v156, v157, v158, s[42:43]
	v_mul_f32_e32 v157, 0x37800000, v156
	v_cndmask_b32_e32 v156, v156, v157, vcc
	v_cmp_class_f32_e32 vcc, v154, v202
	s_nop 1
	v_cndmask_b32_e32 v154, v156, v154, vcc
	v_div_scale_f32 v156, s[4:5], v154, v154, 1.0
	v_rcp_f32_e32 v157, v156
	s_nop 0
	v_fma_f32 v158, -v156, v157, 1.0
	v_fmac_f32_e32 v157, v158, v157
	v_div_scale_f32 v158, vcc, 1.0, v154, 1.0
;     __device__ __forceinline__ void operator()(AccRef acc, int pm, int pn, int z, int wr, int wc, int fr, int fq) const {
;     ...
;         for (int ai = 0; ai < 2; ++ai)
; #pragma unroll
;             for (int m = 0; m < 4; ++m) rrow[ai][m] = 1.0f / sqrtf(rrow[ai][m] * (1.0f / DM) + EPS);
	v_mul_f32_e32 v161, v158, v157
	v_fma_f32 v162, -v156, v161, v158
	v_fmac_f32_e32 v161, v162, v157
	v_fma_f32 v156, -v156, v161, v158
	v_div_fmas_f32 v156, v156, v157, v161
	v_div_fixup_f32 v158, v156, v154, 1.0
	v_fmamk_f32 v154, v159, 0x3a000000, v201
	v_cmp_gt_f32_e32 vcc, s51, v154
	v_mul_f32_e32 v156, 0x4f800000, v154
	s_nop 0
	v_cndmask_b32_e32 v154, v154, v156, vcc
	v_sqrt_f32_e32 v156, v154
	s_nop 0
	v_add_u32_e32 v157, -1, v156
	v_fma_f32 v159, -v157, v156, v154
	v_cmp_ge_f32_e64 s[42:43], 0, v159
	v_add_u32_e32 v159, 1, v156
	s_nop 0
	v_cndmask_b32_e64 v157, v156, v157, s[42:43]
	v_fma_f32 v156, -v159, v156, v154
	v_cmp_lt_f32_e64 s[42:43], 0, v156
	s_nop 1
	v_cndmask_b32_e64 v156, v157, v159, s[42:43]
	v_mul_f32_e32 v157, 0x37800000, v156
	v_cndmask_b32_e32 v156, v156, v157, vcc
	v_cmp_class_f32_e32 vcc, v154, v202
	s_nop 1
	v_cndmask_b32_e32 v154, v156, v154, vcc
	v_div_scale_f32 v156, s[4:5], v154, v154, 1.0
	v_rcp_f32_e32 v157, v156
	s_nop 0
	v_fma_f32 v159, -v156, v157, 1.0
	v_fmac_f32_e32 v157, v159, v157
	v_div_scale_f32 v159, vcc, 1.0, v154, 1.0
	v_mul_f32_e32 v161, v159, v157
	v_fma_f32 v162, -v156, v161, v159
	v_fmac_f32_e32 v161, v162, v157
	v_fma_f32 v156, -v156, v161, v159
	v_div_fmas_f32 v156, v156, v157, v161
	v_div_fixup_f32 v154, v156, v154, 1.0
	v_fmamk_f32 v156, v160, 0x3a000000, v201
	v_cmp_gt_f32_e32 vcc, s51, v156
	v_mul_f32_e32 v157, 0x4f800000, v156
	s_nop 0
	v_cndmask_b32_e32 v156, v156, v157, vcc
	v_sqrt_f32_e32 v157, v156
	s_nop 0
	v_add_u32_e32 v159, -1, v157
	v_fma_f32 v160, -v159, v157, v156
	v_cmp_ge_f32_e64 s[42:43], 0, v160
	v_add_u32_e32 v160, 1, v157
	s_nop 0
	v_cndmask_b32_e64 v159, v157, v159, s[42:43]
	v_fma_f32 v157, -v160, v157, v156
	v_cmp_lt_f32_e64 s[42:43], 0, v157
	s_nop 1
	v_cndmask_b32_e64 v157, v159, v160, s[42:43]
	v_mul_f32_e32 v159, 0x37800000, v157
	v_cndmask_b32_e32 v157, v157, v159, vcc
	v_cmp_class_f32_e32 vcc, v156, v202
	s_nop 1
	v_cndmask_b32_e32 v156, v157, v156, vcc
	v_div_scale_f32 v157, s[4:5], v156, v156, 1.0
	v_rcp_f32_e32 v159, v157
	s_nop 0
	v_fma_f32 v160, -v157, v159, 1.0
	v_fmac_f32_e32 v159, v160, v159
	v_div_scale_f32 v160, vcc, 1.0, v156, 1.0
	v_mul_f32_e32 v161, v160, v159
	v_fma_f32 v162, -v157, v161, v160
	v_fmac_f32_e32 v161, v162, v159
	v_fma_f32 v157, -v157, v161, v160
	v_div_fmas_f32 v157, v157, v159, v161
	v_div_fixup_f32 v156, v157, v156, 1.0
	v_cmp_gt_f32_e32 vcc, s51, v155
	v_mul_f32_e32 v157, 0x4f800000, v155
	s_nop 0
	v_cndmask_b32_e32 v155, v155, v157, vcc
	v_sqrt_f32_e32 v157, v155
	s_nop 0
	v_add_u32_e32 v159, -1, v157
	v_fma_f32 v160, -v159, v157, v155
	v_cmp_ge_f32_e64 s[42:43], 0, v160
	v_add_u32_e32 v160, 1, v157
	s_nop 0
	v_cndmask_b32_e64 v159, v157, v159, s[42:43]
	v_fma_f32 v157, -v160, v157, v155
	v_cmp_lt_f32_e64 s[42:43], 0, v157
	s_nop 1
	v_cndmask_b32_e64 v157, v159, v160, s[42:43]
	v_mul_f32_e32 v159, 0x37800000, v157
	v_cndmask_b32_e32 v157, v157, v159, vcc
	v_cmp_class_f32_e32 vcc, v155, v202
	s_nop 1
	v_cndmask_b32_e32 v155, v157, v155, vcc
	v_div_scale_f32 v157, s[4:5], v155, v155, 1.0
	v_rcp_f32_e32 v159, v157
	s_nop 0
	v_fma_f32 v160, -v157, v159, 1.0
	v_fmac_f32_e32 v159, v160, v159
	v_div_scale_f32 v160, vcc, 1.0, v155, 1.0
	v_mul_f32_e32 v161, v160, v159
	v_fma_f32 v162, -v157, v161, v160
	v_fmac_f32_e32 v161, v162, v159
	v_fma_f32 v157, -v157, v161, v160
	v_div_fmas_f32 v157, v157, v159, v161
	v_div_fixup_f32 v160, v157, v155, 1.0
	v_cmp_gt_f32_e32 vcc, s51, v150
	v_mul_f32_e32 v155, 0x4f800000, v150
	s_nop 0
	v_cndmask_b32_e32 v150, v150, v155, vcc
	v_sqrt_f32_e32 v155, v150
	s_nop 0
	v_add_u32_e32 v157, -1, v155
	v_fma_f32 v159, -v157, v155, v150
	v_cmp_ge_f32_e64 s[42:43], 0, v159
	v_add_u32_e32 v159, 1, v155
	s_nop 0
	v_cndmask_b32_e64 v157, v155, v157, s[42:43]
	v_fma_f32 v155, -v159, v155, v150
	v_cmp_lt_f32_e64 s[42:43], 0, v155
	s_nop 1
	v_cndmask_b32_e64 v155, v157, v159, s[42:43]
	v_mul_f32_e32 v157, 0x37800000, v155
	v_cndmask_b32_e32 v155, v155, v157, vcc
	v_cmp_class_f32_e32 vcc, v150, v202
	s_nop 1
	v_cndmask_b32_e32 v150, v155, v150, vcc
	v_div_scale_f32 v155, s[4:5], v150, v150, 1.0
	v_rcp_f32_e32 v157, v155
	s_nop 0
	v_fma_f32 v159, -v155, v157, 1.0
	v_fmac_f32_e32 v157, v159, v157
	v_div_scale_f32 v159, vcc, 1.0, v150, 1.0
	v_mul_f32_e32 v161, v159, v157
	v_fma_f32 v162, -v155, v161, v159
	v_fmac_f32_e32 v161, v162, v157
	v_fma_f32 v155, -v155, v161, v159
	v_div_fmas_f32 v155, v155, v157, v161
	v_div_fixup_f32 v150, v155, v150, 1.0
	v_cmp_gt_f32_e32 vcc, s51, v148
	v_mul_f32_e32 v155, 0x4f800000, v148
	v_pk_mul_f32 v[60:61], v[60:61], v[150:151] op_sel_hi:[1,0]
	v_cndmask_b32_e32 v148, v148, v155, vcc
	v_sqrt_f32_e32 v155, v148
	v_pk_mul_f32 v[56:57], v[56:57], v[150:151] op_sel_hi:[1,0]
	v_pk_mul_f32 v[58:59], v[58:59], v[150:151] op_sel_hi:[1,0]
	v_pk_mul_f32 v[52:53], v[52:53], v[150:151] op_sel_hi:[1,0]
	v_add_u32_e32 v157, -1, v155
	v_fma_f32 v159, -v157, v155, v148
	v_cmp_ge_f32_e64 s[42:43], 0, v159
	v_add_u32_e32 v159, 1, v155
	v_pk_mul_f32 v[48:49], v[48:49], v[150:151] op_sel_hi:[1,0]
	v_cndmask_b32_e64 v157, v155, v157, s[42:43]
	v_fma_f32 v155, -v159, v155, v148
	v_cmp_lt_f32_e64 s[42:43], 0, v155
	v_pk_mul_f32 v[50:51], v[50:51], v[150:151] op_sel_hi:[1,0]
	s_nop 0
	v_cndmask_b32_e64 v155, v157, v159, s[42:43]
	v_mul_f32_e32 v157, 0x37800000, v155
	v_cndmask_b32_e32 v155, v155, v157, vcc
	v_cmp_class_f32_e32 vcc, v148, v202
	s_nop 1
	v_cndmask_b32_e32 v148, v155, v148, vcc
	v_div_scale_f32 v155, s[4:5], v148, v148, 1.0
	v_rcp_f32_e32 v157, v155
	s_nop 0
	v_fma_f32 v159, -v155, v157, 1.0
	v_fmac_f32_e32 v157, v159, v157
	v_div_scale_f32 v159, vcc, 1.0, v148, 1.0
	v_mul_f32_e32 v161, v159, v157
; __device__ __forceinline__ float fast_sigmoid(float x) { return __builtin_amdgcn_rcpf(1.0f + __builtin_amdgcn_exp2f(-1.44269504f * x)); }
;     __device__ __forceinline__ void operator()(AccRef acc, int pm, int pn, int z, int wr, int wc, int fr, int fq) const {
;     ...
;             for (int m = 0; m < 4; ++m) rrow[ai][m] = 1.0f / sqrtf(rrow[ai][m] * (1.0f / DM) + EPS);
; #pragma unroll
;         for (int ai = 0; ai < 2; ++ai)
; #pragma unroll
;             for (int m = 0; m < 4; ++m) { f32x4 v[2]; const float rr = rrow[ai][m];
; #pragma unroll
;                 for (int n = 0; n < 2; ++n)
; #pragma unroll
;                     for (int j = 0; j < 4; ++j) { const float gt = acc[ai][0][m][n][j] * rr; v[n][j] = gt * fast_sigmoid(gt) * (acc[ai][1][m][n][j] * rr); }
	v_fma_f32 v162, -v155, v161, v159
	v_fmac_f32_e32 v161, v162, v157
	v_fma_f32 v155, -v155, v161, v159
	v_div_fmas_f32 v155, v155, v157, v161
	v_div_fixup_f32 v148, v155, v148, 1.0
	v_cmp_gt_f32_e32 vcc, s51, v144
	v_mul_f32_e32 v155, 0x4f800000, v144
	v_pk_mul_f32 v[44:45], v[44:45], v[148:149] op_sel_hi:[1,0]
	v_cndmask_b32_e32 v144, v144, v155, vcc
	v_sqrt_f32_e32 v155, v144
	v_pk_mul_f32 v[40:41], v[40:41], v[148:149] op_sel_hi:[1,0]
	v_pk_mul_f32 v[42:43], v[42:43], v[148:149] op_sel_hi:[1,0]
	v_pk_mul_f32 v[36:37], v[36:37], v[148:149] op_sel_hi:[1,0]
	v_add_u32_e32 v157, -1, v155
	v_fma_f32 v159, -v157, v155, v144
	v_cmp_ge_f32_e64 s[42:43], 0, v159
	v_add_u32_e32 v159, 1, v155
	v_pk_mul_f32 v[32:33], v[32:33], v[148:149] op_sel_hi:[1,0]
	v_cndmask_b32_e64 v157, v155, v157, s[42:43]
	v_fma_f32 v155, -v159, v155, v144
	v_cmp_lt_f32_e64 s[42:43], 0, v155
	v_pk_mul_f32 v[34:35], v[34:35], v[148:149] op_sel_hi:[1,0]
	s_nop 0
	v_cndmask_b32_e64 v155, v157, v159, s[42:43]
	v_mul_f32_e32 v157, 0x37800000, v155
	v_cndmask_b32_e32 v155, v155, v157, vcc
	v_cmp_class_f32_e32 vcc, v144, v202
	s_nop 1
	v_cndmask_b32_e32 v144, v155, v144, vcc
	v_div_scale_f32 v155, s[4:5], v144, v144, 1.0
	v_rcp_f32_e32 v157, v155
	s_nop 0
	v_fma_f32 v159, -v155, v157, 1.0
	v_fmac_f32_e32 v157, v159, v157
	v_div_scale_f32 v159, vcc, 1.0, v144, 1.0
	v_mul_f32_e32 v161, v159, v157
	v_fma_f32 v162, -v155, v161, v159
	v_fmac_f32_e32 v161, v162, v157
	v_fma_f32 v155, -v155, v161, v159
	v_div_fmas_f32 v155, v155, v157, v161
	v_div_fixup_f32 v144, v155, v144, 1.0
	v_cmp_gt_f32_e32 vcc, s51, v142
	v_mul_f32_e32 v155, 0x4f800000, v142
	v_pk_mul_f32 v[28:29], v[28:29], v[144:145] op_sel_hi:[1,0]
	v_cndmask_b32_e32 v142, v142, v155, vcc
	v_sqrt_f32_e32 v155, v142
	v_pk_mul_f32 v[24:25], v[24:25], v[144:145] op_sel_hi:[1,0]
	v_pk_mul_f32 v[26:27], v[26:27], v[144:145] op_sel_hi:[1,0]
	v_pk_mul_f32 v[20:21], v[20:21], v[144:145] op_sel_hi:[1,0]
	v_add_u32_e32 v157, -1, v155
	v_fma_f32 v159, -v157, v155, v142
	v_cmp_ge_f32_e64 s[42:43], 0, v159
	v_add_u32_e32 v159, 1, v155
	v_pk_mul_f32 v[16:17], v[16:17], v[144:145] op_sel_hi:[1,0]
	v_cndmask_b32_e64 v157, v155, v157, s[42:43]
	v_fma_f32 v155, -v159, v155, v142
	v_cmp_lt_f32_e64 s[42:43], 0, v155
	v_pk_mul_f32 v[18:19], v[18:19], v[144:145] op_sel_hi:[1,0]
	s_nop 0
	v_cndmask_b32_e64 v155, v157, v159, s[42:43]
	v_mul_f32_e32 v157, 0x37800000, v155
	v_cndmask_b32_e32 v155, v155, v157, vcc
	v_cmp_class_f32_e32 vcc, v142, v202
	s_nop 1
	v_cndmask_b32_e32 v142, v155, v142, vcc
	v_div_scale_f32 v155, s[4:5], v142, v142, 1.0
	v_rcp_f32_e32 v157, v155
	s_nop 0
	v_fma_f32 v159, -v155, v157, 1.0
	v_fmac_f32_e32 v157, v159, v157
	v_div_scale_f32 v159, vcc, 1.0, v142, 1.0
	v_mul_f32_e32 v161, v159, v157
	v_fma_f32 v162, -v155, v161, v159
	v_fmac_f32_e32 v161, v162, v157
	v_fma_f32 v155, -v155, v161, v159
	v_div_fmas_f32 v155, v155, v157, v161
	v_pk_mul_f32 v[124:125], v[124:125], v[158:159] op_sel_hi:[1,0]
	v_div_fixup_f32 v142, v155, v142, 1.0
	v_mul_f32_e32 v155, 0xbfb8aa3b, v124
	v_exp_f32_e32 v155, v155
	v_pk_mul_f32 v[120:121], v[120:121], v[158:159] op_sel_hi:[1,0]
	v_pk_mul_f32 v[122:123], v[122:123], v[158:159] op_sel_hi:[1,0]
	v_pk_mul_f32 v[116:117], v[116:117], v[158:159] op_sel_hi:[1,0]
	v_add_f32_e32 v155, 1.0, v155
	v_rcp_f32_e32 v164, v155
	v_mul_f32_e32 v155, 0xbfb8aa3b, v125
	v_exp_f32_e32 v155, v155
	v_pk_mul_f32 v[112:113], v[112:113], v[158:159] op_sel_hi:[1,0]
	v_lshl_or_b32 v162, s22, 7, v149
	v_pk_mul_f32 v[114:115], v[114:115], v[158:159] op_sel_hi:[1,0]
	v_add_f32_e32 v155, 1.0, v155
	v_rcp_f32_e32 v165, v155
	v_ashrrev_i32_e32 v163, 31, v162
	s_movk_i32 s22, 0x2c00
	v_pk_mul_f32 v[108:109], v[108:109], v[154:155] op_sel_hi:[1,0]
	v_pk_mul_f32 v[124:125], v[124:125], v[164:165]
	v_pk_mul_f32 v[104:105], v[104:105], v[154:155] op_sel_hi:[1,0]
	v_pk_mul_f32 v[120:121], v[120:121], v[124:125]
	v_pk_mul_f32 v[124:125], v[126:127], v[158:159] op_sel_hi:[1,0]
	v_pk_mul_f32 v[106:107], v[106:107], v[154:155] op_sel_hi:[1,0]
	v_mul_f32_e32 v126, 0xbfb8aa3b, v124
	v_mul_f32_e32 v127, 0xbfb8aa3b, v125
	v_exp_f32_e32 v126, v126
	v_exp_f32_e32 v127, v127
	v_pk_mul_f32 v[100:101], v[100:101], v[154:155] op_sel_hi:[1,0]
	v_pk_mul_f32 v[96:97], v[96:97], v[154:155] op_sel_hi:[1,0]
	v_add_f32_e32 v126, 1.0, v126
	v_add_f32_e32 v127, 1.0, v127
	v_rcp_f32_e32 v126, v126
	v_rcp_f32_e32 v127, v127
	v_pk_mul_f32 v[98:99], v[98:99], v[154:155] op_sel_hi:[1,0]
	v_pk_mul_f32 v[92:93], v[92:93], v[156:157] op_sel_hi:[1,0]
	v_pk_mul_f32 v[88:89], v[88:89], v[156:157] op_sel_hi:[1,0]
	v_pk_mul_f32 v[124:125], v[124:125], v[126:127]
	v_pk_mul_f32 v[90:91], v[90:91], v[156:157] op_sel_hi:[1,0]
	v_pk_mul_f32 v[122:123], v[122:123], v[124:125]
	v_mul_f32_e32 v124, 0xbfb8aa3b, v116
	v_mul_f32_e32 v125, 0xbfb8aa3b, v117
	v_exp_f32_e32 v124, v124
	v_exp_f32_e32 v125, v125
	v_pk_mul_f32 v[84:85], v[84:85], v[156:157] op_sel_hi:[1,0]
	v_pk_mul_f32 v[80:81], v[80:81], v[156:157] op_sel_hi:[1,0]
	v_add_f32_e32 v124, 1.0, v124
	v_add_f32_e32 v125, 1.0, v125
	v_rcp_f32_e32 v124, v124
	v_rcp_f32_e32 v125, v125
	v_pk_mul_f32 v[82:83], v[82:83], v[156:157] op_sel_hi:[1,0]
	v_pk_mul_f32 v[76:77], v[76:77], v[160:161] op_sel_hi:[1,0]
	v_pk_mul_f32 v[72:73], v[72:73], v[160:161] op_sel_hi:[1,0]
	v_pk_mul_f32 v[116:117], v[116:117], v[124:125]
	v_pk_mul_f32 v[74:75], v[74:75], v[160:161] op_sel_hi:[1,0]
	v_pk_mul_f32 v[112:113], v[112:113], v[116:117]
	v_pk_mul_f32 v[116:117], v[118:119], v[158:159] op_sel_hi:[1,0]
	v_pk_mul_f32 v[68:69], v[68:69], v[160:161] op_sel_hi:[1,0]
	v_mul_f32_e32 v118, 0xbfb8aa3b, v116
	v_mul_f32_e32 v119, 0xbfb8aa3b, v117
; __device__ __forceinline__ float fast_sigmoid(float x) { return __builtin_amdgcn_rcpf(1.0f + __builtin_amdgcn_exp2f(-1.44269504f * x)); }
; __device__ __forceinline__ u32x4 pack8(f32x4 v0, f32x4 v1) { u32x4 w; w.x = cvt_pk_bf16(v0[0], v0[1]); w.y = cvt_pk_bf16(v0[2], v0[3]); w.z = cvt_pk_bf16(v1[0], v1[1]); w.w = cvt_pk_bf16(v1[2], v1[3]); return w; }
;     __device__ __forceinline__ void operator()(AccRef acc, int pm, int pn, int z, int wr, int wc, int fr, int fq) const {
;     ...
;         for (int ai = 0; ai < 2; ++ai)
; #pragma unroll
;             for (int m = 0; m < 4; ++m) { f32x4 v[2]; const float rr = rrow[ai][m];
; #pragma unroll
;                 for (int n = 0; n < 2; ++n)
; #pragma unroll
;                     for (int j = 0; j < 4; ++j) { const float gt = acc[ai][0][m][n][j] * rr; v[n][j] = gt * fast_sigmoid(gt) * (acc[ai][1][m][n][j] * rr); }
;                 *(u32x4*)(Hm + (size_t)(row0 + ai * HALF + m * 16) * DFF + col0) = pack8(v[0], v[1]); }
	v_exp_f32_e32 v118, v118
	v_exp_f32_e32 v119, v119
	v_pk_mul_f32 v[64:65], v[64:65], v[160:161] op_sel_hi:[1,0]
	v_pk_mul_f32 v[66:67], v[66:67], v[160:161] op_sel_hi:[1,0]
	v_add_f32_e32 v118, 1.0, v118
	v_add_f32_e32 v119, 1.0, v119
	v_rcp_f32_e32 v118, v118
	v_rcp_f32_e32 v119, v119
	v_pk_mul_f32 v[12:13], v[12:13], v[142:143] op_sel_hi:[1,0]
	v_pk_mul_f32 v[8:9], v[8:9], v[142:143] op_sel_hi:[1,0]
	v_pk_mul_f32 v[10:11], v[10:11], v[142:143] op_sel_hi:[1,0]
	v_pk_mul_f32 v[116:117], v[116:117], v[118:119]
	v_cvt_pk_bf16_f32 v118, v112, v113
	v_pk_mul_f32 v[114:115], v[114:115], v[116:117]
	v_mov_b64_e32 v[112:113], s[62:63]
	v_cvt_pk_bf16_f32 v116, v120, v121
	v_cvt_pk_bf16_f32 v119, v114, v115
	v_mad_i64_i32 v[120:121], s[4:5], v152, s22, v[112:113]
	v_lshlrev_b64 v[114:115], 1, v[162:163]
	v_cvt_pk_bf16_f32 v117, v122, v123
	v_lshl_add_u64 v[120:121], v[120:121], 0, v[114:115]
	global_store_dwordx4 v[120:121], v[116:119], off
	v_pk_mul_f32 v[4:5], v[4:5], v[142:143] op_sel_hi:[1,0]
	v_pk_mul_f32 v[0:1], v[0:1], v[142:143] op_sel_hi:[1,0]
	v_mul_f32_e32 v116, 0xbfb8aa3b, v108
	v_mul_f32_e32 v117, 0xbfb8aa3b, v109
	v_exp_f32_e32 v116, v116
	v_exp_f32_e32 v117, v117
	v_pk_mul_f32 v[2:3], v[2:3], v[142:143] op_sel_hi:[1,0]
	s_andn2_b64 vcc, exec, s[80:81]
	v_add_f32_e32 v116, 1.0, v116
	v_add_f32_e32 v117, 1.0, v117
	v_rcp_f32_e32 v116, v116
	v_rcp_f32_e32 v117, v117
	s_nop 0
	v_pk_mul_f32 v[108:109], v[108:109], v[116:117]
	s_nop 0
	v_pk_mul_f32 v[104:105], v[104:105], v[108:109]
	v_pk_mul_f32 v[108:109], v[110:111], v[154:155] op_sel_hi:[1,0]
	s_nop 0
	v_mul_f32_e32 v110, 0xbfb8aa3b, v108
	v_mul_f32_e32 v111, 0xbfb8aa3b, v109
	v_exp_f32_e32 v110, v110
	v_exp_f32_e32 v111, v111
	v_add_f32_e32 v110, 1.0, v110
	v_add_f32_e32 v111, 1.0, v111
	v_rcp_f32_e32 v110, v110
	v_rcp_f32_e32 v111, v111
	s_nop 0
	v_pk_mul_f32 v[108:109], v[108:109], v[110:111]
	s_nop 0
	v_pk_mul_f32 v[106:107], v[106:107], v[108:109]
	v_mul_f32_e32 v108, 0xbfb8aa3b, v100
	v_mul_f32_e32 v109, 0xbfb8aa3b, v101
	v_exp_f32_e32 v108, v108
	v_exp_f32_e32 v109, v109
	v_add_f32_e32 v108, 1.0, v108
	v_add_f32_e32 v109, 1.0, v109
	v_rcp_f32_e32 v108, v108
	v_rcp_f32_e32 v109, v109
	s_nop 0
	v_pk_mul_f32 v[100:101], v[100:101], v[108:109]
	s_nop 0
	v_pk_mul_f32 v[100:101], v[96:97], v[100:101]
	v_pk_mul_f32 v[96:97], v[102:103], v[154:155] op_sel_hi:[1,0]
	s_nop 0
	v_mul_f32_e32 v102, 0xbfb8aa3b, v96
	v_mul_f32_e32 v103, 0xbfb8aa3b, v97
	v_exp_f32_e32 v102, v102
	v_exp_f32_e32 v103, v103
	v_add_f32_e32 v102, 1.0, v102
	v_add_f32_e32 v103, 1.0, v103
	v_rcp_f32_e32 v102, v102
	v_rcp_f32_e32 v103, v103
	s_nop 0
	v_pk_mul_f32 v[96:97], v[96:97], v[102:103]
	s_nop 0
	v_pk_mul_f32 v[102:103], v[98:99], v[96:97]
	v_cvt_pk_bf16_f32 v98, v100, v101
	v_mad_i64_i32 v[100:101], s[4:5], v146, s22, v[112:113]
	v_cvt_pk_bf16_f32 v96, v104, v105
	v_cvt_pk_bf16_f32 v97, v106, v107
	v_cvt_pk_bf16_f32 v99, v102, v103
	v_lshl_add_u64 v[100:101], v[100:101], 0, v[114:115]
	global_store_dwordx4 v[100:101], v[96:99], off
	s_nop 1
	v_mul_f32_e32 v96, 0xbfb8aa3b, v92
	v_mul_f32_e32 v97, 0xbfb8aa3b, v93
	v_exp_f32_e32 v96, v96
	v_exp_f32_e32 v97, v97
	v_add_f32_e32 v96, 1.0, v96
	v_add_f32_e32 v97, 1.0, v97
	v_rcp_f32_e32 v96, v96
	v_rcp_f32_e32 v97, v97
	s_nop 0
	v_pk_mul_f32 v[92:93], v[92:93], v[96:97]
	s_nop 0
	v_pk_mul_f32 v[88:89], v[88:89], v[92:93]
	v_pk_mul_f32 v[92:93], v[94:95], v[156:157] op_sel_hi:[1,0]
	s_nop 0
	v_mul_f32_e32 v94, 0xbfb8aa3b, v92
	v_mul_f32_e32 v95, 0xbfb8aa3b, v93
	v_exp_f32_e32 v94, v94
	v_exp_f32_e32 v95, v95
	v_add_f32_e32 v94, 1.0, v94
	v_add_f32_e32 v95, 1.0, v95
	v_rcp_f32_e32 v94, v94
	v_rcp_f32_e32 v95, v95
	s_nop 0
	v_pk_mul_f32 v[92:93], v[92:93], v[94:95]
	s_nop 0
	v_pk_mul_f32 v[90:91], v[90:91], v[92:93]
	v_mul_f32_e32 v92, 0xbfb8aa3b, v84
	v_mul_f32_e32 v93, 0xbfb8aa3b, v85
	v_exp_f32_e32 v92, v92
	v_exp_f32_e32 v93, v93
	v_add_f32_e32 v92, 1.0, v92
	v_add_f32_e32 v93, 1.0, v93
	v_rcp_f32_e32 v92, v92
	v_rcp_f32_e32 v93, v93
	s_nop 0
	v_pk_mul_f32 v[84:85], v[84:85], v[92:93]
	s_nop 0
	v_pk_mul_f32 v[84:85], v[80:81], v[84:85]
	v_pk_mul_f32 v[80:81], v[86:87], v[156:157] op_sel_hi:[1,0]
	s_nop 0
	v_mul_f32_e32 v86, 0xbfb8aa3b, v80
	v_mul_f32_e32 v87, 0xbfb8aa3b, v81
	v_exp_f32_e32 v86, v86
	v_exp_f32_e32 v87, v87
	v_add_f32_e32 v86, 1.0, v86
	v_add_f32_e32 v87, 1.0, v87
	v_rcp_f32_e32 v86, v86
	v_rcp_f32_e32 v87, v87
	s_nop 0
	v_pk_mul_f32 v[80:81], v[80:81], v[86:87]
	s_nop 0
	v_pk_mul_f32 v[86:87], v[82:83], v[80:81]
	v_cvt_pk_bf16_f32 v82, v84, v85
	v_mad_i64_i32 v[84:85], s[4:5], v140, s22, v[112:113]
	v_cvt_pk_bf16_f32 v80, v88, v89
	v_cvt_pk_bf16_f32 v81, v90, v91
	v_cvt_pk_bf16_f32 v83, v86, v87
	v_lshl_add_u64 v[84:85], v[84:85], 0, v[114:115]
	global_store_dwordx4 v[84:85], v[80:83], off
	s_nop 1
	v_mul_f32_e32 v80, 0xbfb8aa3b, v76
	v_mul_f32_e32 v81, 0xbfb8aa3b, v77
	v_exp_f32_e32 v80, v80
	v_exp_f32_e32 v81, v81
	v_add_f32_e32 v80, 1.0, v80
	v_add_f32_e32 v81, 1.0, v81
	v_rcp_f32_e32 v80, v80
	v_rcp_f32_e32 v81, v81
	s_nop 0
	v_pk_mul_f32 v[76:77], v[76:77], v[80:81]
	s_nop 0
	v_pk_mul_f32 v[72:73], v[72:73], v[76:77]
	v_pk_mul_f32 v[76:77], v[78:79], v[160:161] op_sel_hi:[1,0]
	s_nop 0
	v_mul_f32_e32 v78, 0xbfb8aa3b, v76
	v_mul_f32_e32 v79, 0xbfb8aa3b, v77
	v_exp_f32_e32 v78, v78
	v_exp_f32_e32 v79, v79
	v_add_f32_e32 v78, 1.0, v78
	v_add_f32_e32 v79, 1.0, v79
	v_rcp_f32_e32 v78, v78
	v_rcp_f32_e32 v79, v79
	s_nop 0
	v_pk_mul_f32 v[76:77], v[76:77], v[78:79]
	s_nop 0
	v_pk_mul_f32 v[74:75], v[74:75], v[76:77]
	v_mul_f32_e32 v76, 0xbfb8aa3b, v68
	v_mul_f32_e32 v77, 0xbfb8aa3b, v69
	v_exp_f32_e32 v76, v76
	v_exp_f32_e32 v77, v77
; __device__ __forceinline__ float fast_sigmoid(float x) { return __builtin_amdgcn_rcpf(1.0f + __builtin_amdgcn_exp2f(-1.44269504f * x)); }
; __device__ __forceinline__ u32x4 pack8(f32x4 v0, f32x4 v1) { u32x4 w; w.x = cvt_pk_bf16(v0[0], v0[1]); w.y = cvt_pk_bf16(v0[2], v0[3]); w.z = cvt_pk_bf16(v1[0], v1[1]); w.w = cvt_pk_bf16(v1[2], v1[3]); return w; }
;     __device__ __forceinline__ void operator()(AccRef acc, int pm, int pn, int z, int wr, int wc, int fr, int fq) const {
;     ...
;         for (int ai = 0; ai < 2; ++ai)
; #pragma unroll
;             for (int m = 0; m < 4; ++m) { f32x4 v[2]; const float rr = rrow[ai][m];
; #pragma unroll
;                 for (int n = 0; n < 2; ++n)
; #pragma unroll
;                     for (int j = 0; j < 4; ++j) { const float gt = acc[ai][0][m][n][j] * rr; v[n][j] = gt * fast_sigmoid(gt) * (acc[ai][1][m][n][j] * rr); }
;                 *(u32x4*)(Hm + (size_t)(row0 + ai * HALF + m * 16) * DFF + col0) = pack8(v[0], v[1]); }
	v_add_f32_e32 v76, 1.0, v76
	v_add_f32_e32 v77, 1.0, v77
	v_rcp_f32_e32 v76, v76
	v_rcp_f32_e32 v77, v77
	s_nop 0
	v_pk_mul_f32 v[68:69], v[68:69], v[76:77]
	s_nop 0
	v_pk_mul_f32 v[68:69], v[64:65], v[68:69]
	v_pk_mul_f32 v[64:65], v[70:71], v[160:161] op_sel_hi:[1,0]
	s_nop 0
	v_mul_f32_e32 v70, 0xbfb8aa3b, v64
	v_mul_f32_e32 v71, 0xbfb8aa3b, v65
	v_exp_f32_e32 v70, v70
	v_exp_f32_e32 v71, v71
	v_add_f32_e32 v70, 1.0, v70
	v_add_f32_e32 v71, 1.0, v71
	v_rcp_f32_e32 v70, v70
	v_rcp_f32_e32 v71, v71
	s_nop 0
	v_pk_mul_f32 v[64:65], v[64:65], v[70:71]
	s_nop 0
	v_pk_mul_f32 v[70:71], v[66:67], v[64:65]
	v_cvt_pk_bf16_f32 v66, v68, v69
	v_mad_i64_i32 v[68:69], s[4:5], v138, s22, v[112:113]
	v_cvt_pk_bf16_f32 v64, v72, v73
	v_cvt_pk_bf16_f32 v65, v74, v75
	v_cvt_pk_bf16_f32 v67, v70, v71
	v_lshl_add_u64 v[68:69], v[68:69], 0, v[114:115]
	global_store_dwordx4 v[68:69], v[64:67], off
	s_nop 1
	v_mul_f32_e32 v64, 0xbfb8aa3b, v60
	v_mul_f32_e32 v65, 0xbfb8aa3b, v61
	v_exp_f32_e32 v64, v64
	v_exp_f32_e32 v65, v65
	v_add_f32_e32 v64, 1.0, v64
	v_add_f32_e32 v65, 1.0, v65
	v_rcp_f32_e32 v64, v64
	v_rcp_f32_e32 v65, v65
	s_nop 0
	v_pk_mul_f32 v[60:61], v[60:61], v[64:65]
	s_nop 0
	v_pk_mul_f32 v[56:57], v[56:57], v[60:61]
	v_pk_mul_f32 v[60:61], v[62:63], v[150:151] op_sel_hi:[1,0]
	s_nop 0
	v_mul_f32_e32 v62, 0xbfb8aa3b, v60
	v_mul_f32_e32 v63, 0xbfb8aa3b, v61
	v_exp_f32_e32 v62, v62
	v_exp_f32_e32 v63, v63
	v_add_f32_e32 v62, 1.0, v62
	v_add_f32_e32 v63, 1.0, v63
	v_rcp_f32_e32 v62, v62
	v_rcp_f32_e32 v63, v63
	s_nop 0
	v_pk_mul_f32 v[60:61], v[60:61], v[62:63]
	s_nop 0
	v_pk_mul_f32 v[58:59], v[58:59], v[60:61]
	v_mul_f32_e32 v60, 0xbfb8aa3b, v52
	v_mul_f32_e32 v61, 0xbfb8aa3b, v53
	v_exp_f32_e32 v60, v60
	v_exp_f32_e32 v61, v61
	v_add_f32_e32 v60, 1.0, v60
	v_add_f32_e32 v61, 1.0, v61
	v_rcp_f32_e32 v60, v60
	v_rcp_f32_e32 v61, v61
	s_nop 0
	v_pk_mul_f32 v[52:53], v[52:53], v[60:61]
	s_nop 0
	v_pk_mul_f32 v[52:53], v[48:49], v[52:53]
	v_pk_mul_f32 v[48:49], v[54:55], v[150:151] op_sel_hi:[1,0]
	s_nop 0
	v_mul_f32_e32 v54, 0xbfb8aa3b, v48
	v_mul_f32_e32 v55, 0xbfb8aa3b, v49
	v_exp_f32_e32 v54, v54
	v_exp_f32_e32 v55, v55
	v_add_f32_e32 v54, 1.0, v54
	v_add_f32_e32 v55, 1.0, v55
	v_rcp_f32_e32 v54, v54
	v_rcp_f32_e32 v55, v55
	s_nop 0
	v_pk_mul_f32 v[48:49], v[48:49], v[54:55]
	s_nop 0
	v_pk_mul_f32 v[54:55], v[50:51], v[48:49]
	v_cvt_pk_bf16_f32 v50, v52, v53
	v_mad_i64_i32 v[52:53], s[4:5], v153, s22, v[112:113]
	v_cvt_pk_bf16_f32 v48, v56, v57
	v_cvt_pk_bf16_f32 v49, v58, v59
	v_cvt_pk_bf16_f32 v51, v54, v55
	v_lshl_add_u64 v[52:53], v[52:53], 0, v[114:115]
	global_store_dwordx4 v[52:53], v[48:51], off
	s_nop 1
	v_mul_f32_e32 v48, 0xbfb8aa3b, v44
	v_mul_f32_e32 v49, 0xbfb8aa3b, v45
	v_exp_f32_e32 v48, v48
	v_exp_f32_e32 v49, v49
	v_add_f32_e32 v48, 1.0, v48
	v_add_f32_e32 v49, 1.0, v49
	v_rcp_f32_e32 v48, v48
	v_rcp_f32_e32 v49, v49
	s_nop 0
	v_pk_mul_f32 v[44:45], v[44:45], v[48:49]
	s_nop 0
	v_pk_mul_f32 v[40:41], v[40:41], v[44:45]
	v_pk_mul_f32 v[44:45], v[46:47], v[148:149] op_sel_hi:[1,0]
	s_nop 0
	v_mul_f32_e32 v46, 0xbfb8aa3b, v44
	v_mul_f32_e32 v47, 0xbfb8aa3b, v45
	v_exp_f32_e32 v46, v46
	v_exp_f32_e32 v47, v47
	v_add_f32_e32 v46, 1.0, v46
	v_add_f32_e32 v47, 1.0, v47
	v_rcp_f32_e32 v46, v46
	v_rcp_f32_e32 v47, v47
	s_nop 0
	v_pk_mul_f32 v[44:45], v[44:45], v[46:47]
	s_nop 0
	v_pk_mul_f32 v[42:43], v[42:43], v[44:45]
	v_mul_f32_e32 v44, 0xbfb8aa3b, v36
	v_mul_f32_e32 v45, 0xbfb8aa3b, v37
	v_exp_f32_e32 v44, v44
	v_exp_f32_e32 v45, v45
	v_add_f32_e32 v44, 1.0, v44
	v_add_f32_e32 v45, 1.0, v45
	v_rcp_f32_e32 v44, v44
	v_rcp_f32_e32 v45, v45
	s_nop 0
	v_pk_mul_f32 v[36:37], v[36:37], v[44:45]
	s_nop 0
	v_pk_mul_f32 v[36:37], v[32:33], v[36:37]
	v_pk_mul_f32 v[32:33], v[38:39], v[148:149] op_sel_hi:[1,0]
	s_nop 0
	v_mul_f32_e32 v38, 0xbfb8aa3b, v32
	v_mul_f32_e32 v39, 0xbfb8aa3b, v33
	v_exp_f32_e32 v38, v38
	v_exp_f32_e32 v39, v39
	v_add_f32_e32 v38, 1.0, v38
	v_add_f32_e32 v39, 1.0, v39
	v_rcp_f32_e32 v38, v38
; __device__ __forceinline__ float fast_sigmoid(float x) { return __builtin_amdgcn_rcpf(1.0f + __builtin_amdgcn_exp2f(-1.44269504f * x)); }
; #define PG8_BAR __builtin_amdgcn_s_barrier()
; #define PG8_PIN_ACC() do { _Pragma("unroll") for (int a = 0; a < 2; ++a) _Pragma("unroll") for (int b = 0; b < 2; ++b) _Pragma("unroll") for (int m = 0; m < 4; ++m) \
;         asm volatile("" : "+v"(acc[a][b][m][0]), "+v"(acc[a][b][m][1])); } while (0)
; __device__ __forceinline__ u32x4 pack8(f32x4 v0, f32x4 v1) { u32x4 w; w.x = cvt_pk_bf16(v0[0], v0[1]); w.y = cvt_pk_bf16(v0[2], v0[3]); w.z = cvt_pk_bf16(v1[0], v1[1]); w.w = cvt_pk_bf16(v1[2], v1[3]); return w; }
; template <class Epi>
; __device__ __forceinline__ void gemm_phase(LAS unsigned char* lds, const GemmD g, const Epi& E, int G, int c) {
;     ...
;         if (!has_next) break;
;         if constexpr (Epi::PRELOAD) { E.preload(acc, npm, npn, nz, wr, wc, fr, fq); PG8_PIN_ACC(); }
;         else {
; #pragma unroll
;         for (int a = 0; a < 2; ++a)
; #pragma unroll
;             for (int b = 0; b < 2; ++b)
; #pragma unroll
;                 for (int m = 0; m < 4; ++m)
; #pragma unroll
;                     for (int n = 0; n < 2; ++n) acc[a][b][m][n] = (f32x4){0.f, 0.f, 0.f, 0.f};
;         }
;         cpm = npm; cpn = npn; cz = nz; cA = nA; cB = nB; ++ui;
;         if (wr == 1) PG8_BAR;
;     __device__ __forceinline__ void operator()(AccRef acc, int pm, int pn, int z, int wr, int wc, int fr, int fq) const {
;     ...
;         for (int ai = 0; ai < 2; ++ai)
; #pragma unroll
;             for (int m = 0; m < 4; ++m) { f32x4 v[2]; const float rr = rrow[ai][m];
; #pragma unroll
;                 for (int n = 0; n < 2; ++n)
; #pragma unroll
;                     for (int j = 0; j < 4; ++j) { const float gt = acc[ai][0][m][n][j] * rr; v[n][j] = gt * fast_sigmoid(gt) * (acc[ai][1][m][n][j] * rr); }
;                 *(u32x4*)(Hm + (size_t)(row0 + ai * HALF + m * 16) * DFF + col0) = pack8(v[0], v[1]); }
	v_rcp_f32_e32 v39, v39
	s_nop 0
	v_pk_mul_f32 v[32:33], v[32:33], v[38:39]
	s_nop 0
	v_pk_mul_f32 v[38:39], v[34:35], v[32:33]
	v_cvt_pk_bf16_f32 v34, v36, v37
	v_mad_i64_i32 v[36:37], s[4:5], v147, s22, v[112:113]
	v_cvt_pk_bf16_f32 v32, v40, v41
	v_cvt_pk_bf16_f32 v33, v42, v43
	v_cvt_pk_bf16_f32 v35, v38, v39
	v_lshl_add_u64 v[36:37], v[36:37], 0, v[114:115]
	global_store_dwordx4 v[36:37], v[32:35], off
	s_nop 1
	v_mul_f32_e32 v32, 0xbfb8aa3b, v28
	v_mul_f32_e32 v33, 0xbfb8aa3b, v29
	v_exp_f32_e32 v32, v32
	v_exp_f32_e32 v33, v33
	v_add_f32_e32 v32, 1.0, v32
	v_add_f32_e32 v33, 1.0, v33
	v_rcp_f32_e32 v32, v32
	v_rcp_f32_e32 v33, v33
	s_nop 0
	v_pk_mul_f32 v[28:29], v[28:29], v[32:33]
	s_nop 0
	v_pk_mul_f32 v[24:25], v[24:25], v[28:29]
	v_pk_mul_f32 v[28:29], v[30:31], v[144:145] op_sel_hi:[1,0]
	s_nop 0
	v_mul_f32_e32 v30, 0xbfb8aa3b, v28
	v_mul_f32_e32 v31, 0xbfb8aa3b, v29
	v_exp_f32_e32 v30, v30
	v_exp_f32_e32 v31, v31
	v_add_f32_e32 v30, 1.0, v30
	v_add_f32_e32 v31, 1.0, v31
	v_rcp_f32_e32 v30, v30
	v_rcp_f32_e32 v31, v31
	s_nop 0
	v_pk_mul_f32 v[28:29], v[28:29], v[30:31]
	s_nop 0
	v_pk_mul_f32 v[26:27], v[26:27], v[28:29]
	v_mul_f32_e32 v28, 0xbfb8aa3b, v20
	v_mul_f32_e32 v29, 0xbfb8aa3b, v21
	v_exp_f32_e32 v28, v28
	v_exp_f32_e32 v29, v29
	v_add_f32_e32 v28, 1.0, v28
	v_add_f32_e32 v29, 1.0, v29
	v_rcp_f32_e32 v28, v28
	v_rcp_f32_e32 v29, v29
	s_nop 0
	v_pk_mul_f32 v[20:21], v[20:21], v[28:29]
	s_nop 0
	v_pk_mul_f32 v[20:21], v[16:17], v[20:21]
	v_pk_mul_f32 v[16:17], v[22:23], v[144:145] op_sel_hi:[1,0]
	s_nop 0
	v_mul_f32_e32 v22, 0xbfb8aa3b, v16
	v_mul_f32_e32 v23, 0xbfb8aa3b, v17
	v_exp_f32_e32 v22, v22
	v_exp_f32_e32 v23, v23
	v_add_f32_e32 v22, 1.0, v22
	v_add_f32_e32 v23, 1.0, v23
	v_rcp_f32_e32 v22, v22
	v_rcp_f32_e32 v23, v23
	s_nop 0
	v_pk_mul_f32 v[16:17], v[16:17], v[22:23]
	s_nop 0
	v_pk_mul_f32 v[22:23], v[18:19], v[16:17]
	v_cvt_pk_bf16_f32 v18, v20, v21
	v_mad_i64_i32 v[20:21], s[4:5], v141, s22, v[112:113]
	v_cvt_pk_bf16_f32 v16, v24, v25
	v_cvt_pk_bf16_f32 v17, v26, v27
	v_cvt_pk_bf16_f32 v19, v22, v23
	v_lshl_add_u64 v[20:21], v[20:21], 0, v[114:115]
	global_store_dwordx4 v[20:21], v[16:19], off
	s_nop 1
	v_mul_f32_e32 v16, 0xbfb8aa3b, v12
	v_mul_f32_e32 v17, 0xbfb8aa3b, v13
	v_exp_f32_e32 v16, v16
	v_exp_f32_e32 v17, v17
	v_add_f32_e32 v16, 1.0, v16
	v_add_f32_e32 v17, 1.0, v17
	v_rcp_f32_e32 v16, v16
	v_rcp_f32_e32 v17, v17
	s_nop 0
	v_pk_mul_f32 v[12:13], v[12:13], v[16:17]
	s_nop 0
	v_pk_mul_f32 v[8:9], v[8:9], v[12:13]
	v_pk_mul_f32 v[12:13], v[14:15], v[142:143] op_sel_hi:[1,0]
	s_nop 0
	v_mul_f32_e32 v14, 0xbfb8aa3b, v12
	v_mul_f32_e32 v15, 0xbfb8aa3b, v13
	v_exp_f32_e32 v14, v14
	v_exp_f32_e32 v15, v15
	v_add_f32_e32 v14, 1.0, v14
	v_add_f32_e32 v15, 1.0, v15
	v_rcp_f32_e32 v14, v14
	v_rcp_f32_e32 v15, v15
	s_nop 0
	v_pk_mul_f32 v[12:13], v[12:13], v[14:15]
	s_nop 0
	v_pk_mul_f32 v[10:11], v[10:11], v[12:13]
	v_mul_f32_e32 v12, 0xbfb8aa3b, v4
	v_mul_f32_e32 v13, 0xbfb8aa3b, v5
	v_exp_f32_e32 v12, v12
	v_exp_f32_e32 v13, v13
	v_add_f32_e32 v12, 1.0, v12
	v_add_f32_e32 v13, 1.0, v13
	v_rcp_f32_e32 v12, v12
	v_rcp_f32_e32 v13, v13
	s_nop 0
	v_pk_mul_f32 v[4:5], v[4:5], v[12:13]
	s_nop 0
	v_pk_mul_f32 v[4:5], v[0:1], v[4:5]
	v_pk_mul_f32 v[0:1], v[6:7], v[142:143] op_sel_hi:[1,0]
	s_nop 0
	v_mul_f32_e32 v6, 0xbfb8aa3b, v0
	v_mul_f32_e32 v7, 0xbfb8aa3b, v1
	v_exp_f32_e32 v6, v6
	v_exp_f32_e32 v7, v7
	v_add_f32_e32 v6, 1.0, v6
	v_add_f32_e32 v7, 1.0, v7
	v_rcp_f32_e32 v6, v6
	v_rcp_f32_e32 v7, v7
	s_nop 0
	v_pk_mul_f32 v[0:1], v[0:1], v[6:7]
	s_nop 0
	v_pk_mul_f32 v[6:7], v[2:3], v[0:1]
	v_cvt_pk_bf16_f32 v2, v4, v5
	v_mad_i64_i32 v[4:5], s[4:5], v139, s22, v[112:113]
	v_cvt_pk_bf16_f32 v0, v8, v9
	v_cvt_pk_bf16_f32 v1, v10, v11
	v_cvt_pk_bf16_f32 v3, v6, v7
	v_lshl_add_u64 v[4:5], v[4:5], 0, v[114:115]
	s_mov_b64 s[4:5], -1
	global_store_dwordx4 v[4:5], v[0:3], off
	s_cbranch_vccnz .LBB0_198
	s_andn2_b64 vcc, exec, s[44:45]
	s_cbranch_vccnz .LBB0_197
	s_barrier
	s_branch .LBB0_197

; __device__ __forceinline__ bool unit_at(const GemmD& g, int G, int c, int i, int& pm, int& pn, int& z) {
;     const int L = i * G + c; const int per = g.nM * g.nN; if (L >= per * g.nZ) return false;
;     z = L / per; int wgid = L % per;
;     { const int q = per / NXCD, r = per % NXCD, xcd = wgid % NXCD, off = wgid / NXCD; wgid = (xcd < r ? xcd * (q + 1) : r * (q + 1) + (xcd - r) * q) + off; }
;     const int nig = WGM * g.nN, gid = wgid / nig, fm = gid * WGM, gsz = (g.nM - fm) < WGM ? (g.nM - fm) : WGM;
;     pm = fm + ((wgid % nig) % gsz); pn = (wgid % nig) / gsz; return true;
;     __device__ __forceinline__ void operator()(AccRef acc, int pm, int pn, int z, int wr, int wc, int fr, int fq) const {
;         const int h = z & 3; const float lf2 = lg[h] * 1.44269504f, lb2 = lg[4 + h] * 1.44269504f;
.LBB0_318:
	s_and_b32 s100, s86, 3
	s_lshl_b32 s100, s100, 2
	s_load_dword s98, s[46:47], s100
	s_add_i32 s100, s100, 16
	s_load_dword s101, s[46:47], s100
	s_add_i32 s22, s22, 1
	v_readlane_b32 s4, v240, 0
	s_mul_i32 s19, s22, s4
	s_add_i32 s19, s19, s53
	v_readlane_b32 s5, v240, 1
	s_cmpk_lt_i32 s19, 0x800
	s_cselect_b64 s[4:5], -1, 0
	s_cmpk_gt_i32 s19, 0x7ff
	s_cbranch_scc1 .LBB0_324
	s_ashr_i32 s17, s19, 31
	s_lshr_b32 s17, s17, 26
	s_add_i32 s17, s19, s17
	s_and_b32 s27, s17, 0xffc0
	s_sub_i32 s27, s19, s27
	s_bfe_i32 s19, s27, 0x80000
	s_bfe_u32 s19, s19, 0x3000c
	s_add_i32 s19, s27, s19
	s_and_b32 s28, s19, 0xf8
	s_sub_i32 s27, s27, s28
	s_bfe_i32 s28, s27, 0x80000
	s_sext_i32_i16 s27, s28
	s_cmp_gt_i32 s27, -1
	s_mov_b64 s[42:43], -1
	s_cbranch_scc0 .LBB0_321
	s_lshl_b32 s27, s28, 3
	s_mov_b64 s[42:43], 0

; __device__ __forceinline__ u32x4 pack8(f32x4 v0, f32x4 v1) { u32x4 w; w.x = cvt_pk_bf16(v0[0], v0[1]); w.y = cvt_pk_bf16(v0[2], v0[3]); w.z = cvt_pk_bf16(v1[0], v1[1]); w.w = cvt_pk_bf16(v1[2], v1[3]); return w; }
;     __device__ __forceinline__ void operator()(AccRef acc, int pm, int pn, int z, int wr, int wc, int fr, int fq) const {
;         const int h = z & 3; const float lf2 = lg[h] * 1.44269504f, lb2 = lg[4 + h] * 1.44269504f;
;         const int row0 = pm * BM + wr * 64 + fr, col0 = pn * BM + wc * 32 + 8 * fq;
;         bf16_t* Pz = P + (size_t)z * SEQ * SEQ;
;         if (pm == pn) {
; #pragma unroll
;             for (int ai = 0; ai < 2; ++ai)
; #pragma unroll
;                 for (int m = 0; m < 4; ++m) { const int row = row0 + ai * HALF + m * 16; bf16_t* rowp = Pz + (size_t)row * SEQ + col0;
; #pragma unroll
;                     for (int bj = 0; bj < 2; ++bj) { f32x4 v[2];
; #pragma unroll
;                         for (int n = 0; n < 2; ++n)
; #pragma unroll
;                             for (int j = 0; j < 4; ++j) { const int d = row - (col0 + bj * HALF + 4 * n + j); const float l2 = d >= 0 ? lf2 : lb2; const float ad = (float)(d >= 0 ? d : -d);
;                                 v[n][j] = acc[ai][bj][m][n][j] * __builtin_amdgcn_exp2f(l2 * ad); }
;                         *(u32x4*)(rowp + bj * HALF) = pack8(v[0], v[1]); } }
;         } else {
;             const bool fwd = pm > pn; const float l2 = fwd ? lf2 : lb2; const int piv = (fwd ? pm : pn) * BM;
;             f32x4 cf[2][2];
; #pragma unroll
;             for (int bj = 0; bj < 2; ++bj)
; #pragma unroll
;                 for (int n = 0; n < 2; ++n)
; #pragma unroll
;                     for (int j = 0; j < 4; ++j) { const int col = col0 + bj * HALF + 4 * n + j; cf[bj][n][j] = __builtin_amdgcn_exp2f(l2 * (float)(fwd ? piv - col : col - piv)); }
.LBB0_332:
	s_and_b32 s4, s86, 3
	s_lshl_b32 s4, s4, 2
	v_mov_b32_e32 v128, s4
	s_ashr_i32 s87, s86, 31
	s_lshl_b64 s[4:5], s[86:87], 23
	v_lshl_add_u32 v154, s2, 8, v170
	s_add_u32 s82, s14, s4
	v_lshl_or_b32 v140, s6, 8, v172
	s_addc_u32 s83, s15, s5
	v_or_b32_e32 v152, 16, v154
	v_or_b32_e32 v150, 32, v154
	v_or_b32_e32 v148, 48, v154
	v_add_u32_e32 v146, 0x80, v154
	s_mov_b64 s[4:5], -1
	s_cmp_lg_u32 s2, s6
	v_or_b32_e32 v194, 1, v140
	v_or_b32_e32 v193, 2, v140
	v_or_b32_e32 v192, 3, v140
	v_or_b32_e32 v191, 4, v140
	v_or_b32_e32 v190, 5, v140
	v_or_b32_e32 v189, 6, v140
	v_or_b32_e32 v188, 7, v140
	v_or_b32_e32 v187, 0x80, v140
	v_or_b32_e32 v186, 0x81, v140
	v_or_b32_e32 v185, 0x82, v140
	v_or_b32_e32 v184, 0x83, v140
	v_or_b32_e32 v183, 0x84, v140
	v_or_b32_e32 v182, 0x85, v140
	v_or_b32_e32 v181, 0x86, v140
	v_or_b32_e32 v180, 0x87, v140
	v_ashrrev_i32_e32 v141, 31, v140
	v_ashrrev_i32_e32 v155, 31, v154
	v_ashrrev_i32_e32 v153, 31, v152
	v_ashrrev_i32_e32 v151, 31, v150
	v_ashrrev_i32_e32 v149, 31, v148
	v_ashrrev_i32_e32 v147, 31, v146
	v_add_u32_e32 v144, 0x90, v154
	v_add_u32_e32 v142, 0xa0, v154
	v_add_u32_e32 v138, 0xb0, v154
	s_waitcnt lgkmcnt(0)
	v_mov_b32_e32 v129, s98
	v_mov_b32_e32 v128, s101
	v_mul_f32_e32 v174, 0x3fb8aa3b, v129
	v_mul_f32_e32 v175, 0x3fb8aa3b, v128
	s_cbranch_scc0 .LBB0_334
	s_cmp_gt_i32 s2, s6
	s_cselect_b64 vcc, -1, 0
	s_max_i32 s2, s2, s6
	s_lshl_b32 s2, s2, 8
	v_sub_u32_e32 v128, s2, v140
	v_subrev_u32_e32 v129, s2, v140
	v_cndmask_b32_e32 v128, v129, v128, vcc
	v_sub_u32_e32 v129, s2, v194
	v_subrev_u32_e32 v130, s2, v194
	v_cndmask_b32_e32 v129, v130, v129, vcc
	v_sub_u32_e32 v130, s2, v193
	v_subrev_u32_e32 v131, s2, v193
	v_cndmask_b32_e32 v130, v131, v130, vcc
	v_sub_u32_e32 v131, s2, v192
	v_subrev_u32_e32 v143, s2, v192
	v_cndmask_b32_e32 v131, v143, v131, vcc
	v_sub_u32_e32 v143, s2, v191
	v_subrev_u32_e32 v145, s2, v191
	v_cndmask_b32_e32 v143, v145, v143, vcc
	v_sub_u32_e32 v145, s2, v190
	v_subrev_u32_e32 v156, s2, v190
	v_cvt_f32_i32_e32 v143, v143
	v_cndmask_b32_e32 v145, v156, v145, vcc
	v_sub_u32_e32 v156, s2, v189
	v_subrev_u32_e32 v157, s2, v189
	v_cvt_f32_i32_e32 v145, v145
	v_cndmask_b32_e32 v156, v157, v156, vcc
	v_cvt_f32_i32_e32 v156, v156
	v_cndmask_b32_e32 v139, v175, v174, vcc
	v_mul_f32_e32 v143, v139, v143
	v_exp_f32_e32 v158, v143
	v_mul_f32_e32 v143, v139, v145
	v_exp_f32_e32 v159, v143
	v_mul_f32_e32 v143, v139, v156
	v_sub_u32_e32 v145, s2, v188
	v_subrev_u32_e32 v156, s2, v188
	v_cndmask_b32_e32 v145, v156, v145, vcc
	v_sub_u32_e32 v156, s2, v187
	v_subrev_u32_e32 v157, s2, v187
	v_cvt_f32_i32_e32 v145, v145
	v_cndmask_b32_e32 v156, v157, v156, vcc
	v_cvt_f32_i32_e32 v156, v156
	v_exp_f32_e32 v160, v143
	v_mul_f32_e32 v143, v139, v145
	v_exp_f32_e32 v161, v143
	v_mul_f32_e32 v143, v139, v156
	v_sub_u32_e32 v145, s2, v186
	v_subrev_u32_e32 v156, s2, v186
	v_cndmask_b32_e32 v145, v156, v145, vcc
	v_sub_u32_e32 v156, s2, v185
	v_subrev_u32_e32 v157, s2, v185
	v_cvt_f32_i32_e32 v145, v145
	v_cndmask_b32_e32 v156, v157, v156, vcc
	v_cvt_f32_i32_e32 v156, v156
	v_exp_f32_e32 v162, v143
	v_mul_f32_e32 v143, v139, v145
	v_exp_f32_e32 v163, v143
	v_mul_f32_e32 v143, v139, v156
	v_sub_u32_e32 v145, s2, v184
	v_subrev_u32_e32 v156, s2, v184
	v_cndmask_b32_e32 v145, v156, v145, vcc
	v_sub_u32_e32 v156, s2, v183
	v_subrev_u32_e32 v157, s2, v183
	v_cvt_f32_i32_e32 v145, v145
	v_cndmask_b32_e32 v156, v157, v156, vcc
	v_cvt_f32_i32_e32 v156, v156
	v_exp_f32_e32 v164, v143
	v_mul_f32_e32 v143, v139, v145
	v_exp_f32_e32 v165, v143
	v_mul_f32_e32 v143, v139, v156
	v_sub_u32_e32 v145, s2, v182
	v_subrev_u32_e32 v156, s2, v182
	v_cndmask_b32_e32 v145, v156, v145, vcc
	v_sub_u32_e32 v156, s2, v181
	v_subrev_u32_e32 v157, s2, v181
	v_cvt_f32_i32_e32 v145, v145
	v_cndmask_b32_e32 v156, v157, v156, vcc
	v_cvt_f32_i32_e32 v156, v156
	v_exp_f32_e32 v166, v143
	v_mul_f32_e32 v143, v139, v145
	v_exp_f32_e32 v167, v143
	v_mul_f32_e32 v143, v139, v156
	v_sub_u32_e32 v145, s2, v180
	v_subrev_u32_e32 v156, s2, v180
	v_cndmask_b32_e32 v145, v156, v145, vcc
	v_subrev_u32_e32 v156, s2, v154
	v_sub_u32_e32 v157, s2, v154
	v_cvt_f32_i32_e32 v145, v145
	v_cndmask_b32_e32 v156, v157, v156, vcc
	v_cvt_f32_i32_e32 v128, v128
	v_cvt_f32_i32_e32 v129, v129
	v_cvt_f32_i32_e32 v130, v130
	v_cvt_f32_i32_e32 v131, v131
	v_cvt_f32_i32_e32 v156, v156
	v_exp_f32_e32 v168, v143
	v_mul_f32_e32 v143, v139, v145
	v_mul_f32_e32 v128, v139, v128
	v_mul_f32_e32 v129, v139, v129
	v_mul_f32_e32 v130, v139, v130
	v_mul_f32_e32 v131, v139, v131
	v_exp_f32_e32 v169, v143
	v_mul_f32_e32 v143, v139, v156
	v_exp_f32_e32 v128, v128
	v_exp_f32_e32 v129, v129
	v_exp_f32_e32 v130, v130
	v_exp_f32_e32 v131, v131
	v_exp_f32_e32 v196, v143
	v_subrev_u32_e32 v143, s2, v152
	v_sub_u32_e32 v145, s2, v152
	v_cndmask_b32_e32 v143, v145, v143, vcc
	v_cvt_f32_i32_e32 v143, v143
	v_pk_mul_f32 v[210:211], v[196:197], v[128:129] op_sel_hi:[0,1]
	v_pk_mul_f32 v[212:213], v[196:197], v[130:131] op_sel_hi:[0,1]
	v_pk_mul_f32 v[214:215], v[196:197], v[158:159] op_sel_hi:[0,1]
	v_pk_mul_f32 v[216:217], v[196:197], v[160:161] op_sel_hi:[0,1]
	v_lshl_add_u64 v[156:157], v[140:141], 1, s[82:83]
	v_lshlrev_b64 v[198:199], 12, v[154:155]
	v_pk_mul_f32 v[212:213], v[126:127], v[212:213]
	v_pk_mul_f32 v[210:211], v[124:125], v[210:211]
	v_pk_mul_f32 v[216:217], v[122:123], v[216:217]
	v_pk_mul_f32 v[214:215], v[120:121], v[214:215]
	v_lshl_add_u64 v[198:199], v[156:157], 0, v[198:199]
	v_cvt_pk_bf16_f32 v210, v210, v211
	v_cvt_pk_bf16_f32 v211, v212, v213
	v_cvt_pk_bf16_f32 v212, v214, v215
	v_cvt_pk_bf16_f32 v213, v216, v217
	v_mul_f32_e32 v143, v139, v143
; __device__ __forceinline__ u32x4 pack8(f32x4 v0, f32x4 v1) { u32x4 w; w.x = cvt_pk_bf16(v0[0], v0[1]); w.y = cvt_pk_bf16(v0[2], v0[3]); w.z = cvt_pk_bf16(v1[0], v1[1]); w.w = cvt_pk_bf16(v1[2], v1[3]); return w; }
;     __device__ __forceinline__ void operator()(AccRef acc, int pm, int pn, int z, int wr, int wc, int fr, int fq) const {
;     ...
;             for (int ai = 0; ai < 2; ++ai)
; #pragma unroll
;                 for (int m = 0; m < 4; ++m) { const int row = row0 + ai * HALF + m * 16; bf16_t* rowp = Pz + (size_t)row * SEQ + col0;
;                     const float rf = __builtin_amdgcn_exp2f(l2 * (float)(fwd ? row - piv : piv - row));
; #pragma unroll
;                     for (int bj = 0; bj < 2; ++bj) *(u32x4*)(rowp + bj * HALF) = pack8(acc[ai][bj][m][0] * (cf[bj][0] * rf), acc[ai][bj][m][1] * (cf[bj][1] * rf)); }
	global_store_dwordx4 v[198:199], v[210:213], off
	v_pk_mul_f32 v[214:215], v[196:197], v[166:167] op_sel_hi:[0,1]
	v_pk_mul_f32 v[216:217], v[196:197], v[168:169] op_sel_hi:[0,1]
	v_pk_mul_f32 v[210:211], v[196:197], v[162:163] op_sel_hi:[0,1]
	v_pk_mul_f32 v[212:213], v[196:197], v[164:165] op_sel_hi:[0,1]
	v_exp_f32_e32 v196, v143
	v_subrev_u32_e32 v143, s2, v150
	v_sub_u32_e32 v145, s2, v150
	v_cndmask_b32_e32 v143, v145, v143, vcc
	v_pk_mul_f32 v[212:213], v[118:119], v[212:213]
	v_pk_mul_f32 v[210:211], v[116:117], v[210:211]
	v_pk_mul_f32 v[216:217], v[114:115], v[216:217]
	v_pk_mul_f32 v[214:215], v[112:113], v[214:215]
	v_cvt_f32_i32_e32 v143, v143
	v_cvt_pk_bf16_f32 v210, v210, v211
	v_cvt_pk_bf16_f32 v211, v212, v213
	v_cvt_pk_bf16_f32 v212, v214, v215
	v_cvt_pk_bf16_f32 v213, v216, v217
	global_store_dwordx4 v[198:199], v[210:213], off offset:256
	v_pk_mul_f32 v[214:215], v[196:197], v[158:159] op_sel_hi:[0,1]
	v_pk_mul_f32 v[216:217], v[196:197], v[160:161] op_sel_hi:[0,1]
	v_pk_mul_f32 v[210:211], v[196:197], v[128:129] op_sel_hi:[0,1]
	v_pk_mul_f32 v[212:213], v[196:197], v[130:131] op_sel_hi:[0,1]
	v_lshlrev_b64 v[198:199], 12, v[152:153]
	v_pk_mul_f32 v[212:213], v[110:111], v[212:213]
	v_pk_mul_f32 v[210:211], v[108:109], v[210:211]
	v_pk_mul_f32 v[216:217], v[106:107], v[216:217]
	v_pk_mul_f32 v[214:215], v[104:105], v[214:215]
	v_lshl_add_u64 v[198:199], v[156:157], 0, v[198:199]
	v_cvt_pk_bf16_f32 v210, v210, v211
	v_cvt_pk_bf16_f32 v211, v212, v213
	v_cvt_pk_bf16_f32 v212, v214, v215
	v_cvt_pk_bf16_f32 v213, v216, v217
	v_mul_f32_e32 v143, v139, v143
	global_store_dwordx4 v[198:199], v[210:213], off
	v_pk_mul_f32 v[214:215], v[196:197], v[166:167] op_sel_hi:[0,1]
	v_pk_mul_f32 v[216:217], v[196:197], v[168:169] op_sel_hi:[0,1]
	v_pk_mul_f32 v[210:211], v[196:197], v[162:163] op_sel_hi:[0,1]
	v_pk_mul_f32 v[212:213], v[196:197], v[164:165] op_sel_hi:[0,1]
	v_exp_f32_e32 v196, v143
	v_subrev_u32_e32 v143, s2, v148
	v_sub_u32_e32 v145, s2, v148
	v_cndmask_b32_e32 v143, v145, v143, vcc
	v_pk_mul_f32 v[212:213], v[102:103], v[212:213]
	v_pk_mul_f32 v[210:211], v[100:101], v[210:211]
	v_pk_mul_f32 v[216:217], v[98:99], v[216:217]
	v_pk_mul_f32 v[214:215], v[96:97], v[214:215]
	v_cvt_f32_i32_e32 v143, v143
	v_cvt_pk_bf16_f32 v210, v210, v211
	v_cvt_pk_bf16_f32 v211, v212, v213
	v_cvt_pk_bf16_f32 v212, v214, v215
	v_cvt_pk_bf16_f32 v213, v216, v217
	global_store_dwordx4 v[198:199], v[210:213], off offset:256
	v_pk_mul_f32 v[214:215], v[196:197], v[158:159] op_sel_hi:[0,1]
	v_pk_mul_f32 v[216:217], v[196:197], v[160:161] op_sel_hi:[0,1]
	v_pk_mul_f32 v[210:211], v[196:197], v[128:129] op_sel_hi:[0,1]
	v_pk_mul_f32 v[212:213], v[196:197], v[130:131] op_sel_hi:[0,1]
	v_lshlrev_b64 v[198:199], 12, v[150:151]
	v_pk_mul_f32 v[212:213], v[94:95], v[212:213]
	v_pk_mul_f32 v[210:211], v[92:93], v[210:211]
	v_pk_mul_f32 v[216:217], v[90:91], v[216:217]
	v_pk_mul_f32 v[214:215], v[88:89], v[214:215]
	v_lshl_add_u64 v[198:199], v[156:157], 0, v[198:199]
	v_cvt_pk_bf16_f32 v210, v210, v211
	v_cvt_pk_bf16_f32 v211, v212, v213
	v_cvt_pk_bf16_f32 v212, v214, v215
	v_cvt_pk_bf16_f32 v213, v216, v217
	v_mul_f32_e32 v143, v139, v143
	global_store_dwordx4 v[198:199], v[210:213], off
	v_pk_mul_f32 v[214:215], v[196:197], v[166:167] op_sel_hi:[0,1]
	v_pk_mul_f32 v[216:217], v[196:197], v[168:169] op_sel_hi:[0,1]
	v_pk_mul_f32 v[210:211], v[196:197], v[162:163] op_sel_hi:[0,1]
	v_pk_mul_f32 v[212:213], v[196:197], v[164:165] op_sel_hi:[0,1]
	v_exp_f32_e32 v196, v143
	v_subrev_u32_e32 v143, s2, v146
	v_sub_u32_e32 v145, s2, v146
	v_cndmask_b32_e32 v143, v145, v143, vcc
	v_pk_mul_f32 v[212:213], v[86:87], v[212:213]
	v_pk_mul_f32 v[210:211], v[84:85], v[210:211]
	v_pk_mul_f32 v[216:217], v[82:83], v[216:217]
	v_pk_mul_f32 v[214:215], v[80:81], v[214:215]
	v_cvt_f32_i32_e32 v143, v143
	v_cvt_pk_bf16_f32 v210, v210, v211
	v_cvt_pk_bf16_f32 v211, v212, v213
	v_cvt_pk_bf16_f32 v212, v214, v215
	v_cvt_pk_bf16_f32 v213, v216, v217
	global_store_dwordx4 v[198:199], v[210:213], off offset:256
	v_pk_mul_f32 v[214:215], v[196:197], v[158:159] op_sel_hi:[0,1]
	v_pk_mul_f32 v[216:217], v[196:197], v[160:161] op_sel_hi:[0,1]
	v_pk_mul_f32 v[210:211], v[196:197], v[128:129] op_sel_hi:[0,1]
	v_pk_mul_f32 v[212:213], v[196:197], v[130:131] op_sel_hi:[0,1]
	v_lshlrev_b64 v[198:199], 12, v[148:149]
	v_pk_mul_f32 v[212:213], v[78:79], v[212:213]
	v_pk_mul_f32 v[210:211], v[76:77], v[210:211]
	v_pk_mul_f32 v[216:217], v[74:75], v[216:217]
	v_pk_mul_f32 v[214:215], v[72:73], v[214:215]
	v_lshl_add_u64 v[198:199], v[156:157], 0, v[198:199]
	v_cvt_pk_bf16_f32 v210, v210, v211
	v_cvt_pk_bf16_f32 v211, v212, v213
	v_cvt_pk_bf16_f32 v212, v214, v215
	v_cvt_pk_bf16_f32 v213, v216, v217
	v_mul_f32_e32 v143, v139, v143
	global_store_dwordx4 v[198:199], v[210:213], off
	v_pk_mul_f32 v[214:215], v[196:197], v[166:167] op_sel_hi:[0,1]
	v_pk_mul_f32 v[216:217], v[196:197], v[168:169] op_sel_hi:[0,1]
	v_pk_mul_f32 v[210:211], v[196:197], v[162:163] op_sel_hi:[0,1]
	v_pk_mul_f32 v[212:213], v[196:197], v[164:165] op_sel_hi:[0,1]
	v_exp_f32_e32 v196, v143
	v_subrev_u32_e32 v143, s2, v144
	v_sub_u32_e32 v145, s2, v144
	v_pk_mul_f32 v[212:213], v[70:71], v[212:213]
	v_pk_mul_f32 v[210:211], v[68:69], v[210:211]
	v_pk_mul_f32 v[216:217], v[66:67], v[216:217]
	v_pk_mul_f32 v[214:215], v[64:65], v[214:215]
	v_cndmask_b32_e32 v143, v145, v143, vcc
	v_cvt_pk_bf16_f32 v210, v210, v211
	v_cvt_pk_bf16_f32 v211, v212, v213
	v_cvt_pk_bf16_f32 v212, v214, v215
	v_cvt_pk_bf16_f32 v213, v216, v217
	v_cvt_f32_i32_e32 v143, v143
	global_store_dwordx4 v[198:199], v[210:213], off offset:256
; __device__ __forceinline__ u32x4 pack8(f32x4 v0, f32x4 v1) { u32x4 w; w.x = cvt_pk_bf16(v0[0], v0[1]); w.y = cvt_pk_bf16(v0[2], v0[3]); w.z = cvt_pk_bf16(v1[0], v1[1]); w.w = cvt_pk_bf16(v1[2], v1[3]); return w; }
;     __device__ __forceinline__ void operator()(AccRef acc, int pm, int pn, int z, int wr, int wc, int fr, int fq) const {
;     ...
;             for (int ai = 0; ai < 2; ++ai)
; #pragma unroll
;                 for (int m = 0; m < 4; ++m) { const int row = row0 + ai * HALF + m * 16; bf16_t* rowp = Pz + (size_t)row * SEQ + col0;
;                     const float rf = __builtin_amdgcn_exp2f(l2 * (float)(fwd ? row - piv : piv - row));
; #pragma unroll
;                     for (int bj = 0; bj < 2; ++bj) *(u32x4*)(rowp + bj * HALF) = pack8(acc[ai][bj][m][0] * (cf[bj][0] * rf), acc[ai][bj][m][1] * (cf[bj][1] * rf)); }
	v_pk_mul_f32 v[214:215], v[196:197], v[158:159] op_sel_hi:[0,1]
	v_pk_mul_f32 v[216:217], v[196:197], v[160:161] op_sel_hi:[0,1]
	v_pk_mul_f32 v[210:211], v[196:197], v[128:129] op_sel_hi:[0,1]
	v_pk_mul_f32 v[212:213], v[196:197], v[130:131] op_sel_hi:[0,1]
	v_lshlrev_b64 v[198:199], 12, v[146:147]
	v_pk_mul_f32 v[212:213], v[62:63], v[212:213]
	v_pk_mul_f32 v[210:211], v[60:61], v[210:211]
	v_pk_mul_f32 v[216:217], v[58:59], v[216:217]
	v_pk_mul_f32 v[214:215], v[56:57], v[214:215]
	v_lshl_add_u64 v[198:199], v[156:157], 0, v[198:199]
	v_cvt_pk_bf16_f32 v210, v210, v211
	v_cvt_pk_bf16_f32 v211, v212, v213
	v_cvt_pk_bf16_f32 v212, v214, v215
	v_cvt_pk_bf16_f32 v213, v216, v217
	global_store_dwordx4 v[198:199], v[210:213], off
	v_pk_mul_f32 v[214:215], v[196:197], v[166:167] op_sel_hi:[0,1]
	v_pk_mul_f32 v[216:217], v[196:197], v[168:169] op_sel_hi:[0,1]
	v_pk_mul_f32 v[210:211], v[196:197], v[162:163] op_sel_hi:[0,1]
	v_pk_mul_f32 v[212:213], v[196:197], v[164:165] op_sel_hi:[0,1]
	v_mul_f32_e32 v143, v139, v143
	v_pk_mul_f32 v[212:213], v[54:55], v[212:213]
	v_pk_mul_f32 v[210:211], v[52:53], v[210:211]
	v_pk_mul_f32 v[216:217], v[50:51], v[216:217]
	v_pk_mul_f32 v[214:215], v[48:49], v[214:215]
	v_exp_f32_e32 v196, v143
	v_cvt_pk_bf16_f32 v210, v210, v211
	v_cvt_pk_bf16_f32 v211, v212, v213
	v_cvt_pk_bf16_f32 v212, v214, v215
	v_cvt_pk_bf16_f32 v213, v216, v217
	v_ashrrev_i32_e32 v145, 31, v144
	global_store_dwordx4 v[198:199], v[210:213], off offset:256
	v_lshlrev_b64 v[198:199], 12, v[144:145]
	v_subrev_u32_e32 v143, s2, v142
	v_sub_u32_e32 v145, s2, v142
	v_cndmask_b32_e32 v143, v145, v143, vcc
	v_pk_mul_f32 v[210:211], v[196:197], v[128:129] op_sel_hi:[0,1]
	v_pk_mul_f32 v[212:213], v[196:197], v[130:131] op_sel_hi:[0,1]
	v_pk_mul_f32 v[214:215], v[196:197], v[158:159] op_sel_hi:[0,1]
	v_pk_mul_f32 v[216:217], v[196:197], v[160:161] op_sel_hi:[0,1]
	v_cvt_f32_i32_e32 v143, v143
	v_pk_mul_f32 v[212:213], v[46:47], v[212:213]
	v_pk_mul_f32 v[210:211], v[44:45], v[210:211]
	v_pk_mul_f32 v[216:217], v[42:43], v[216:217]
	v_pk_mul_f32 v[214:215], v[40:41], v[214:215]
	v_lshl_add_u64 v[198:199], v[156:157], 0, v[198:199]
	v_cvt_pk_bf16_f32 v210, v210, v211
	v_cvt_pk_bf16_f32 v211, v212, v213
	v_cvt_pk_bf16_f32 v212, v214, v215
	v_cvt_pk_bf16_f32 v213, v216, v217
	global_store_dwordx4 v[198:199], v[210:213], off
	v_pk_mul_f32 v[214:215], v[196:197], v[166:167] op_sel_hi:[0,1]
	v_pk_mul_f32 v[216:217], v[196:197], v[168:169] op_sel_hi:[0,1]
	v_pk_mul_f32 v[210:211], v[196:197], v[162:163] op_sel_hi:[0,1]
	v_pk_mul_f32 v[212:213], v[196:197], v[164:165] op_sel_hi:[0,1]
	v_pk_mul_f32 v[212:213], v[38:39], v[212:213]
	v_pk_mul_f32 v[210:211], v[36:37], v[210:211]
	v_pk_mul_f32 v[216:217], v[34:35], v[216:217]
	v_pk_mul_f32 v[214:215], v[32:33], v[214:215]
	v_mul_f32_e32 v143, v139, v143
	v_cvt_pk_bf16_f32 v210, v210, v211
	v_cvt_pk_bf16_f32 v211, v212, v213
	v_cvt_pk_bf16_f32 v212, v214, v215
	v_cvt_pk_bf16_f32 v213, v216, v217
	v_exp_f32_e32 v196, v143
	v_ashrrev_i32_e32 v143, 31, v142
	global_store_dwordx4 v[198:199], v[210:213], off offset:256
	v_lshlrev_b64 v[198:199], 12, v[142:143]
	v_subrev_u32_e32 v143, s2, v138
	v_sub_u32_e32 v145, s2, v138
	v_cndmask_b32_e32 v143, v145, v143, vcc
	v_cvt_f32_i32_e32 v143, v143
	v_pk_mul_f32 v[210:211], v[196:197], v[128:129] op_sel_hi:[0,1]
	v_pk_mul_f32 v[212:213], v[196:197], v[130:131] op_sel_hi:[0,1]
	v_pk_mul_f32 v[214:215], v[196:197], v[158:159] op_sel_hi:[0,1]
	v_pk_mul_f32 v[216:217], v[196:197], v[160:161] op_sel_hi:[0,1]
	v_pk_mul_f32 v[212:213], v[30:31], v[212:213]
	v_pk_mul_f32 v[210:211], v[28:29], v[210:211]
	v_pk_mul_f32 v[216:217], v[26:27], v[216:217]
	v_pk_mul_f32 v[214:215], v[24:25], v[214:215]
	v_lshl_add_u64 v[198:199], v[156:157], 0, v[198:199]
	v_cvt_pk_bf16_f32 v210, v210, v211
	v_cvt_pk_bf16_f32 v211, v212, v213
	v_cvt_pk_bf16_f32 v212, v214, v215
	v_cvt_pk_bf16_f32 v213, v216, v217
	v_mul_f32_e32 v139, v139, v143
	global_store_dwordx4 v[198:199], v[210:213], off
	v_pk_mul_f32 v[214:215], v[196:197], v[166:167] op_sel_hi:[0,1]
	v_pk_mul_f32 v[216:217], v[196:197], v[168:169] op_sel_hi:[0,1]
	v_pk_mul_f32 v[210:211], v[196:197], v[162:163] op_sel_hi:[0,1]
	v_pk_mul_f32 v[212:213], v[196:197], v[164:165] op_sel_hi:[0,1]
	v_exp_f32_e32 v196, v139
	v_pk_mul_f32 v[212:213], v[22:23], v[212:213]
	v_pk_mul_f32 v[210:211], v[20:21], v[210:211]
	v_pk_mul_f32 v[216:217], v[18:19], v[216:217]
	v_pk_mul_f32 v[214:215], v[16:17], v[214:215]
	v_cvt_pk_bf16_f32 v210, v210, v211
	v_cvt_pk_bf16_f32 v211, v212, v213
	v_cvt_pk_bf16_f32 v212, v214, v215
	v_cvt_pk_bf16_f32 v213, v216, v217
	v_ashrrev_i32_e32 v139, 31, v138
	v_pk_mul_f32 v[128:129], v[196:197], v[128:129] op_sel_hi:[0,1]
	v_pk_mul_f32 v[130:131], v[196:197], v[130:131] op_sel_hi:[0,1]
	v_pk_mul_f32 v[158:159], v[196:197], v[158:159] op_sel_hi:[0,1]
	v_pk_mul_f32 v[160:161], v[196:197], v[160:161] op_sel_hi:[0,1]
	global_store_dwordx4 v[198:199], v[210:213], off offset:256
	v_lshlrev_b64 v[198:199], 12, v[138:139]
	v_pk_mul_f32 v[130:131], v[14:15], v[130:131]
	v_pk_mul_f32 v[128:129], v[12:13], v[128:129]
	v_pk_mul_f32 v[160:161], v[10:11], v[160:161]
	v_pk_mul_f32 v[158:159], v[8:9], v[158:159]
	v_lshl_add_u64 v[156:157], v[156:157], 0, v[198:199]
	v_cvt_pk_bf16_f32 v128, v128, v129
	v_cvt_pk_bf16_f32 v129, v130, v131
	v_cvt_pk_bf16_f32 v130, v158, v159
	v_cvt_pk_bf16_f32 v131, v160, v161
	global_store_dwordx4 v[156:157], v[128:131], off
	v_pk_mul_f32 v[160:161], v[196:197], v[166:167] op_sel_hi:[0,1]
	s_mov_b64 s[4:5], 0
	v_pk_mul_f32 v[128:129], v[196:197], v[162:163] op_sel_hi:[0,1]
	v_pk_mul_f32 v[130:131], v[196:197], v[164:165] op_sel_hi:[0,1]
	v_pk_mul_f32 v[128:129], v[4:5], v[128:129]
	v_pk_mul_f32 v[158:159], v[6:7], v[130:131]
	v_pk_mul_f32 v[162:163], v[196:197], v[168:169] op_sel_hi:[0,1]
	v_cvt_pk_bf16_f32 v128, v128, v129

; __global__ void __launch_bounds__(512, 2) mega_fwd(Params p_) {
	.amdhsa_kernel _Z8mega_fwd6Params
		.amdhsa_group_segment_fixed_size 0
		.amdhsa_private_segment_fixed_size 0
		.amdhsa_kernarg_size 440
		.amdhsa_user_sgpr_count 2
		.amdhsa_user_sgpr_dispatch_ptr 0
		.amdhsa_user_sgpr_queue_ptr 0
		.amdhsa_user_sgpr_kernarg_segment_ptr 1
		.amdhsa_user_sgpr_dispatch_id 0
		.amdhsa_user_sgpr_kernarg_preload_length 0
		.amdhsa_user_sgpr_kernarg_preload_offset 0
		.amdhsa_user_sgpr_private_segment_size 0
		.amdhsa_uses_dynamic_stack 0
		.amdhsa_enable_private_segment 0
		.amdhsa_system_sgpr_workgroup_id_x 1
		.amdhsa_system_sgpr_workgroup_id_y 0
		.amdhsa_system_sgpr_workgroup_id_z 0
		.amdhsa_system_sgpr_workgroup_info 0
		.amdhsa_system_vgpr_workitem_id 2
		.amdhsa_next_free_vgpr 252
		.amdhsa_next_free_sgpr 102
		.amdhsa_accum_offset 252
		.amdhsa_reserve_vcc 1
		.amdhsa_float_round_mode_32 0
		.amdhsa_float_round_mode_16_64 0
		.amdhsa_float_denorm_mode_32 3
		.amdhsa_float_denorm_mode_16_64 3
		.amdhsa_dx10_clamp 1
		.amdhsa_ieee_mode 1
		.amdhsa_fp16_overflow 0
		.amdhsa_tg_split 0
		.amdhsa_exception_fp_ieee_invalid_op 0
		.amdhsa_exception_fp_denorm_src 0
		.amdhsa_exception_fp_ieee_div_zero 0
		.amdhsa_exception_fp_ieee_overflow 0
		.amdhsa_exception_fp_ieee_underflow 0
		.amdhsa_exception_fp_ieee_inexact 0
		.amdhsa_exception_int_div_zero 0
	.end_amdhsa_kernel

; __global__ void __launch_bounds__(512, 2) mega_fwd(Params p_) {
amdhsa.kernels:
  - .agpr_count:     0
    .args:
      - .offset:         0
        .size:           184
        .value_kind:     by_value
      - .offset:         184
        .size:           4
        .value_kind:     hidden_block_count_x
      - .offset:         188
        .size:           4
        .value_kind:     hidden_block_count_y
      - .offset:         192
        .size:           4
        .value_kind:     hidden_block_count_z
      - .offset:         196
        .size:           2
        .value_kind:     hidden_group_size_x
      - .offset:         198
        .size:           2
        .value_kind:     hidden_group_size_y
      - .offset:         200
        .size:           2
        .value_kind:     hidden_group_size_z
      - .offset:         202
        .size:           2
        .value_kind:     hidden_remainder_x
      - .offset:         204
        .size:           2
        .value_kind:     hidden_remainder_y
      - .offset:         206
        .size:           2
        .value_kind:     hidden_remainder_z
      - .offset:         224
        .size:           8
        .value_kind:     hidden_global_offset_x
      - .offset:         232
        .size:           8
        .value_kind:     hidden_global_offset_y
      - .offset:         240
        .size:           8
        .value_kind:     hidden_global_offset_z
      - .offset:         248
        .size:           2
        .value_kind:     hidden_grid_dims
      - .offset:         272
        .size:           8
        .value_kind:     hidden_multigrid_sync_arg
      - .offset:         304
        .size:           4
        .value_kind:     hidden_dynamic_lds_size
    .group_segment_fixed_size: 0
    .kernarg_segment_align: 8
    .kernarg_segment_size: 440
    .language:       OpenCL C
    .language_version:
      - 2
      - 0
    .max_flat_workgroup_size: 512
    .name:           _Z8mega_fwd6Params
    .private_segment_fixed_size: 0
    .sgpr_count:     108
    .sgpr_spill_count: 200
    .symbol:         _Z8mega_fwd6Params.kd
    .uniform_work_group_size: 1
    .uses_dynamic_stack: false
    .vgpr_count:     252
    .vgpr_spill_count: 0
    .wavefront_size: 64
